# attention S phase: all Q fragments preloaded once (shared by both key halves) instead of 32 load-wait round trips; K-fragment LDS reads 4-deep in first half (on top of v55)
# baseline (speedup 1.0000x reference)
; #define LAS __attribute__((address_space(3)))
; __device__ __forceinline__ int opaque_tid() { int t = threadIdx.x; asm volatile("" : "+v"(t)); return t; }
; __device__ void attn_item(const bf16_t* __restrict__ QX, const bf16_t* __restrict__ KV, bf16_t* __restrict__ O, int tt, int head, LAS unsigned char* lds) {
;   const int tid = opaque_tid(), w = tid >> 6, l = tid & 63; const int row0 = tt * 256; const int b = tt < 64 ? (tt >> 3) : 8; const int mrow0 = b * 256;
;   constexpr unsigned KS = 528, VS = 576;
; #pragma unroll 4
;   for (int it = 0; it < 16; ++it) { const int q = tid + it * 512, m = q >> 5, c = q & 31;
;     *(LAS u32x4*)(lds + m * KS + c * 16) = *(const u32x4*)(KV + (size_t)(mrow0 + m) * 2048 + head * 256 + c * 8); }
;   __syncthreads();
;   const int il = l & 31, h = l >> 5, i16 = l & 15, q4 = i16 >> 2, p4 = i16 & 3, G1 = (l >> 4) & 1;
;   const int row = row0 + w * 32 + il;
;   bf16x8 pf[8][2];
;   float mxp = -3.0e38f, sum = 0.f;
;   const bf16_t* qp = QX + (size_t)row * 1024 + head * 256 + 8 * h;
; #pragma unroll
;   for (int hf = 0; hf < 2; ++hf) {
;     f32x16 sc[4];
; #pragma unroll
;     for (int i = 0; i < 4; ++i) sc[i] = (f32x16){};
.LBB0_982:
	v_readlane_b32 s20, v255, 62
	v_readlane_b32 s12, v255, 61
	s_min_i32 s7, s20, 64
	s_lshl_b32 s22, s12, 8
	s_lshl_b32 s7, s7, 5
	s_ashr_i32 s23, s22, 31
	v_mov_b32_e32 v133, v214
	s_and_b32 s7, s7, 0xffffff00
	s_lshl_b64 s[34:35], s[22:23], 1
	s_add_u32 s12, s14, s34
	v_and_b32_e32 v0, 31, v133
	s_addc_u32 s13, s15, s35
	v_lshlrev_b32_e32 v160, 4, v0
	v_lshl_add_u64 v[128:129], s[12:13], 0, v[160:161]
	v_add_u32_e32 v132, 0, v160
	v_lshrrev_b32_e32 v1, 5, v133
	v_add_u32_e32 v2, s7, v1
	v_ashrrev_i32_e32 v3, 31, v2
	v_lshlrev_b64 v[2:3], 12, v[2:3]
	v_lshl_add_u64 v[2:3], v[128:129], 0, v[2:3]
	v_mad_u32_u24 v6, v1, s59, v132
	s_mov_b64 s[36:37], 0x10000
	v_add_u32_e32 v7, 0x10800, v6
	global_load_dwordx4 v[8:11], v[2:3], off
	v_lshl_add_u64 v[2:3], v[2:3], 0, s[36:37]
	global_load_dwordx4 v[12:15], v[2:3], off
	v_lshl_add_u64 v[2:3], v[2:3], 0, s[36:37]
	global_load_dwordx4 v[16:19], v[2:3], off
	v_lshl_add_u64 v[2:3], v[2:3], 0, s[36:37]
	global_load_dwordx4 v[20:23], v[2:3], off
	v_lshl_add_u64 v[2:3], v[2:3], 0, s[36:37]
	global_load_dwordx4 v[24:27], v[2:3], off
	v_lshl_add_u64 v[2:3], v[2:3], 0, s[36:37]
	global_load_dwordx4 v[28:31], v[2:3], off
	v_lshl_add_u64 v[2:3], v[2:3], 0, s[36:37]
	global_load_dwordx4 v[32:35], v[2:3], off
	v_lshl_add_u64 v[2:3], v[2:3], 0, s[36:37]
	global_load_dwordx4 v[36:39], v[2:3], off
	v_lshl_add_u64 v[2:3], v[2:3], 0, s[36:37]
	global_load_dwordx4 v[40:43], v[2:3], off
	v_lshl_add_u64 v[2:3], v[2:3], 0, s[36:37]
	global_load_dwordx4 v[44:47], v[2:3], off
	v_lshl_add_u64 v[2:3], v[2:3], 0, s[36:37]
	global_load_dwordx4 v[48:51], v[2:3], off
	v_lshl_add_u64 v[2:3], v[2:3], 0, s[36:37]
	global_load_dwordx4 v[52:55], v[2:3], off
	v_lshl_add_u64 v[2:3], v[2:3], 0, s[36:37]
	global_load_dwordx4 v[56:59], v[2:3], off
	v_lshl_add_u64 v[2:3], v[2:3], 0, s[36:37]
	global_load_dwordx4 v[60:63], v[2:3], off
	v_lshl_add_u64 v[2:3], v[2:3], 0, s[36:37]
	global_load_dwordx4 v[64:67], v[2:3], off
	v_lshl_add_u64 v[2:3], v[2:3], 0, s[36:37]
	global_load_dwordx4 v[68:71], v[2:3], off
	s_waitcnt vmcnt(15)
	ds_write_b128 v6, v[8:11]
	s_waitcnt vmcnt(14)
	ds_write_b128 v6, v[12:15] offset:8448
	s_waitcnt vmcnt(13)
	ds_write_b128 v6, v[16:19] offset:16896
	s_waitcnt vmcnt(12)
	ds_write_b128 v6, v[20:23] offset:25344
	s_waitcnt vmcnt(11)
	ds_write_b128 v6, v[24:27] offset:33792
	s_waitcnt vmcnt(10)
	ds_write_b128 v6, v[28:31] offset:42240
	s_waitcnt vmcnt(9)
	ds_write_b128 v6, v[32:35] offset:50688
	s_waitcnt vmcnt(8)
	ds_write_b128 v6, v[36:39] offset:59136
	s_waitcnt vmcnt(7)
	ds_write_b128 v7, v[40:43]
	s_waitcnt vmcnt(6)
	ds_write_b128 v7, v[44:47] offset:8448
	s_waitcnt vmcnt(5)
	ds_write_b128 v7, v[48:51] offset:16896
	s_waitcnt vmcnt(4)
	ds_write_b128 v7, v[52:55] offset:25344
	s_waitcnt vmcnt(3)
	ds_write_b128 v7, v[56:59] offset:33792
	s_waitcnt vmcnt(2)
	ds_write_b128 v7, v[60:63] offset:42240
	s_waitcnt vmcnt(1)
	ds_write_b128 v7, v[64:67] offset:50688
	s_waitcnt vmcnt(0)
	ds_write_b128 v7, v[68:71] offset:59136
	s_movk_i32 s12, 0x2000
	v_ashrrev_i32_e32 v1, 1, v133
	v_and_b32_e32 v1, 0xffffffe0, v1
	v_lshl_add_u32 v1, s20, 8, v1
	v_or_b32_e32 v130, v1, v0
	v_bfe_u32 v136, v133, 5, 1
	v_ashrrev_i32_e32 v131, 31, v130
	v_readlane_b32 s12, v255, 44
	v_mul_u32_u24_e32 v2, 0x210, v0
	v_lshlrev_b32_e32 v160, 4, v136
	v_lshlrev_b64 v[0:1], 11, v[130:131]
	s_add_u32 s12, s12, s34
	v_readlane_b32 s13, v255, 45
	v_or_b32_e32 v0, v0, v160
	s_addc_u32 s13, s13, s35
	v_lshl_add_u64 v[134:135], s[12:13], 0, v[0:1]
	v_mov_b32_e32 v0, 0
	v_add3_u32 v138, v2, v160, 0
	s_mov_b32 s12, 0
	v_mov_b64_e32 v[64:65], v[134:135]
	v_mov_b32_e32 v1, v0
	v_mov_b32_e32 v2, v0
	v_mov_b32_e32 v3, v0
	v_mov_b32_e32 v4, v0
	v_mov_b32_e32 v5, v0
	v_mov_b32_e32 v6, v0
	v_mov_b32_e32 v7, v0
	v_mov_b32_e32 v8, v0
	v_mov_b32_e32 v9, v0
	v_mov_b32_e32 v10, v0
	v_mov_b32_e32 v11, v0
	v_mov_b32_e32 v12, v0
	v_mov_b32_e32 v13, v0
	v_mov_b32_e32 v14, v0
	v_mov_b32_e32 v15, v0
	v_mov_b32_e32 v16, v0
	v_mov_b32_e32 v17, v0
	v_mov_b32_e32 v18, v0
	v_mov_b32_e32 v19, v0
	v_mov_b32_e32 v20, v0
	v_mov_b32_e32 v21, v0
	v_mov_b32_e32 v22, v0
	v_mov_b32_e32 v23, v0
	v_mov_b32_e32 v24, v0
	v_mov_b32_e32 v25, v0
	v_mov_b32_e32 v26, v0
	v_mov_b32_e32 v27, v0
	v_mov_b32_e32 v28, v0
	v_mov_b32_e32 v29, v0
	v_mov_b32_e32 v30, v0
	v_mov_b32_e32 v31, v0
	v_mov_b32_e32 v32, v0
	v_mov_b32_e32 v33, v0
	v_mov_b32_e32 v34, v0
	v_mov_b32_e32 v35, v0
	v_mov_b32_e32 v36, v0
	v_mov_b32_e32 v37, v0
	v_mov_b32_e32 v38, v0
	v_mov_b32_e32 v39, v0
	v_mov_b32_e32 v40, v0
	v_mov_b32_e32 v41, v0
	v_mov_b32_e32 v42, v0
	v_mov_b32_e32 v43, v0
	v_mov_b32_e32 v44, v0
	v_mov_b32_e32 v45, v0
	v_mov_b32_e32 v46, v0
	v_mov_b32_e32 v47, v0
	v_mov_b32_e32 v48, v0
	v_mov_b32_e32 v49, v0
	v_mov_b32_e32 v50, v0
	v_mov_b32_e32 v51, v0
	v_mov_b32_e32 v52, v0
	v_mov_b32_e32 v53, v0
	v_mov_b32_e32 v54, v0
	v_mov_b32_e32 v55, v0
	v_mov_b32_e32 v56, v0
	v_mov_b32_e32 v57, v0
	v_mov_b32_e32 v58, v0
	v_mov_b32_e32 v59, v0
	v_mov_b32_e32 v60, v0
	v_mov_b32_e32 v61, v0
	v_mov_b32_e32 v62, v0
	v_mov_b32_e32 v63, v0
	s_waitcnt lgkmcnt(0)
	s_barrier
; #define LAS __attribute__((address_space(3)))
; __device__ __forceinline__ f32x16 mfma32(bf16x8 a, bf16x8 b, f32x16 c) { return __builtin_amdgcn_mfma_f32_32x32x16_bf16(a, b, c, 0, 0, 0); }
; __device__ void attn_item(const bf16_t* __restrict__ QX, const bf16_t* __restrict__ KV, bf16_t* __restrict__ O, int tt, int head, LAS unsigned char* lds) {
;     ...
;   for (int hf = 0; hf < 2; ++hf) {
;     f32x16 sc[4];
; #pragma unroll
;     for (int i = 0; i < 4; ++i) sc[i] = (f32x16){};
; #pragma unroll 4
;     for (int ks = 0; ks < 16; ++ks) {
;       const bf16x8 B = *(const bf16x8*)(qp + 16 * ks);
; #pragma unroll
;       for (int mt = 0; mt < 4; ++mt) sc[mt] = mfma32(*(const LAS bf16x8*)(lds + ((hf * 4 + mt) * 32 + il) * KS + (16 * ks + 8 * h) * 2), B, sc[mt]);
;     }
	global_load_dwordx4 v[150:153], v[64:65], off offset:-64
	global_load_dwordx4 v[154:157], v[64:65], off offset:-32
	global_load_dwordx4 v[174:177], v[64:65], off
	global_load_dwordx4 v[178:181], v[64:65], off offset:32
	global_load_dwordx4 v[182:185], v[64:65], off offset:64
	global_load_dwordx4 v[186:189], v[64:65], off offset:96
	global_load_dwordx4 v[190:193], v[64:65], off offset:128
	global_load_dwordx4 v[194:197], v[64:65], off offset:160
	global_load_dwordx4 v[198:201], v[64:65], off offset:192
	global_load_dwordx4 v[202:205], v[64:65], off offset:224
	global_load_dwordx4 v[206:209], v[64:65], off offset:256
	global_load_dwordx4 v[226:229], v[64:65], off offset:288
	global_load_dwordx4 v[232:235], v[64:65], off offset:320
	global_load_dwordx4 v[236:239], v[64:65], off offset:352
	global_load_dwordx4 v[240:243], v[64:65], off offset:384
	global_load_dwordx4 v[66:69], v[64:65], off offset:416
	ds_read_b128 v[70:73], v138 offset:0
	ds_read_b128 v[74:77], v138 offset:16896
	ds_read_b128 v[78:81], v138 offset:33792
	ds_read_b128 v[82:85], v138 offset:50688
	s_waitcnt vmcnt(15)
	s_waitcnt lgkmcnt(3)
	v_mfma_f32_32x32x16_bf16 v[48:63], v[70:73], v[150:153], v[48:63]
	ds_read_b128 v[70:73], v138 offset:32
	s_waitcnt lgkmcnt(3)
	v_mfma_f32_32x32x16_bf16 v[32:47], v[74:77], v[150:153], v[32:47]
	ds_read_b128 v[74:77], v138 offset:16928
	s_waitcnt lgkmcnt(3)
	v_mfma_f32_32x32x16_bf16 v[16:31], v[78:81], v[150:153], v[16:31]
	ds_read_b128 v[78:81], v138 offset:33824
	s_waitcnt lgkmcnt(3)
	v_mfma_f32_32x32x16_bf16 v[0:15], v[82:85], v[150:153], v[0:15]
	ds_read_b128 v[82:85], v138 offset:50720
	s_waitcnt vmcnt(14)
	s_waitcnt lgkmcnt(3)
	v_mfma_f32_32x32x16_bf16 v[48:63], v[70:73], v[154:157], v[48:63]
	ds_read_b128 v[70:73], v138 offset:64
	s_waitcnt lgkmcnt(3)
	v_mfma_f32_32x32x16_bf16 v[32:47], v[74:77], v[154:157], v[32:47]
	ds_read_b128 v[74:77], v138 offset:16960
	s_waitcnt lgkmcnt(3)
	v_mfma_f32_32x32x16_bf16 v[16:31], v[78:81], v[154:157], v[16:31]
	ds_read_b128 v[78:81], v138 offset:33856
	s_waitcnt lgkmcnt(3)
	v_mfma_f32_32x32x16_bf16 v[0:15], v[82:85], v[154:157], v[0:15]
	ds_read_b128 v[82:85], v138 offset:50752
	s_waitcnt vmcnt(13)
	s_waitcnt lgkmcnt(3)
	v_mfma_f32_32x32x16_bf16 v[48:63], v[70:73], v[174:177], v[48:63]
	ds_read_b128 v[70:73], v138 offset:96
	s_waitcnt lgkmcnt(3)
	v_mfma_f32_32x32x16_bf16 v[32:47], v[74:77], v[174:177], v[32:47]
	ds_read_b128 v[74:77], v138 offset:16992
	s_waitcnt lgkmcnt(3)
	v_mfma_f32_32x32x16_bf16 v[16:31], v[78:81], v[174:177], v[16:31]
	ds_read_b128 v[78:81], v138 offset:33888
	s_waitcnt lgkmcnt(3)
	v_mfma_f32_32x32x16_bf16 v[0:15], v[82:85], v[174:177], v[0:15]
	ds_read_b128 v[82:85], v138 offset:50784
	s_waitcnt vmcnt(12)
	s_waitcnt lgkmcnt(3)
	v_mfma_f32_32x32x16_bf16 v[48:63], v[70:73], v[178:181], v[48:63]
	ds_read_b128 v[70:73], v138 offset:128
	s_waitcnt lgkmcnt(3)
	v_mfma_f32_32x32x16_bf16 v[32:47], v[74:77], v[178:181], v[32:47]
	ds_read_b128 v[74:77], v138 offset:17024
	s_waitcnt lgkmcnt(3)
	v_mfma_f32_32x32x16_bf16 v[16:31], v[78:81], v[178:181], v[16:31]
	ds_read_b128 v[78:81], v138 offset:33920
	s_waitcnt lgkmcnt(3)
	v_mfma_f32_32x32x16_bf16 v[0:15], v[82:85], v[178:181], v[0:15]
	ds_read_b128 v[82:85], v138 offset:50816
	s_waitcnt vmcnt(11)
	s_waitcnt lgkmcnt(3)
	v_mfma_f32_32x32x16_bf16 v[48:63], v[70:73], v[182:185], v[48:63]
	ds_read_b128 v[70:73], v138 offset:160
	s_waitcnt lgkmcnt(3)
	v_mfma_f32_32x32x16_bf16 v[32:47], v[74:77], v[182:185], v[32:47]
	ds_read_b128 v[74:77], v138 offset:17056
	s_waitcnt lgkmcnt(3)
	v_mfma_f32_32x32x16_bf16 v[16:31], v[78:81], v[182:185], v[16:31]
	ds_read_b128 v[78:81], v138 offset:33952
	s_waitcnt lgkmcnt(3)
	v_mfma_f32_32x32x16_bf16 v[0:15], v[82:85], v[182:185], v[0:15]
	ds_read_b128 v[82:85], v138 offset:50848
	s_waitcnt vmcnt(10)
	s_waitcnt lgkmcnt(3)
	v_mfma_f32_32x32x16_bf16 v[48:63], v[70:73], v[186:189], v[48:63]
	ds_read_b128 v[70:73], v138 offset:192
	s_waitcnt lgkmcnt(3)
	v_mfma_f32_32x32x16_bf16 v[32:47], v[74:77], v[186:189], v[32:47]
	ds_read_b128 v[74:77], v138 offset:17088
	s_waitcnt lgkmcnt(3)
	v_mfma_f32_32x32x16_bf16 v[16:31], v[78:81], v[186:189], v[16:31]
	ds_read_b128 v[78:81], v138 offset:33984
	s_waitcnt lgkmcnt(3)
	v_mfma_f32_32x32x16_bf16 v[0:15], v[82:85], v[186:189], v[0:15]
	ds_read_b128 v[82:85], v138 offset:50880
	s_waitcnt vmcnt(9)
	s_waitcnt lgkmcnt(3)
	v_mfma_f32_32x32x16_bf16 v[48:63], v[70:73], v[190:193], v[48:63]
	ds_read_b128 v[70:73], v138 offset:224
	s_waitcnt lgkmcnt(3)
	v_mfma_f32_32x32x16_bf16 v[32:47], v[74:77], v[190:193], v[32:47]
	ds_read_b128 v[74:77], v138 offset:17120
	s_waitcnt lgkmcnt(3)
	v_mfma_f32_32x32x16_bf16 v[16:31], v[78:81], v[190:193], v[16:31]
	ds_read_b128 v[78:81], v138 offset:34016
	s_waitcnt lgkmcnt(3)
	v_mfma_f32_32x32x16_bf16 v[0:15], v[82:85], v[190:193], v[0:15]
	ds_read_b128 v[82:85], v138 offset:50912
	s_waitcnt vmcnt(8)
	s_waitcnt lgkmcnt(3)
	v_mfma_f32_32x32x16_bf16 v[48:63], v[70:73], v[194:197], v[48:63]
	ds_read_b128 v[70:73], v138 offset:256
	s_waitcnt lgkmcnt(3)
	v_mfma_f32_32x32x16_bf16 v[32:47], v[74:77], v[194:197], v[32:47]
	ds_read_b128 v[74:77], v138 offset:17152
	s_waitcnt lgkmcnt(3)
	v_mfma_f32_32x32x16_bf16 v[16:31], v[78:81], v[194:197], v[16:31]
	ds_read_b128 v[78:81], v138 offset:34048
	s_waitcnt lgkmcnt(3)
	v_mfma_f32_32x32x16_bf16 v[0:15], v[82:85], v[194:197], v[0:15]
	ds_read_b128 v[82:85], v138 offset:50944
	s_waitcnt vmcnt(7)
	s_waitcnt lgkmcnt(3)
	v_mfma_f32_32x32x16_bf16 v[48:63], v[70:73], v[198:201], v[48:63]
	ds_read_b128 v[70:73], v138 offset:288
	s_waitcnt lgkmcnt(3)
	v_mfma_f32_32x32x16_bf16 v[32:47], v[74:77], v[198:201], v[32:47]
	ds_read_b128 v[74:77], v138 offset:17184
	s_waitcnt lgkmcnt(3)
; #define LAS __attribute__((address_space(3)))
; __device__ __forceinline__ f32x16 mfma32(bf16x8 a, bf16x8 b, f32x16 c) { return __builtin_amdgcn_mfma_f32_32x32x16_bf16(a, b, c, 0, 0, 0); }
; __device__ void attn_item(const bf16_t* __restrict__ QX, const bf16_t* __restrict__ KV, bf16_t* __restrict__ O, int tt, int head, LAS unsigned char* lds) {
;     ...
;     for (int i = 0; i < 4; ++i) sc[i] = (f32x16){};
; #pragma unroll 4
;     for (int ks = 0; ks < 16; ++ks) {
;       const bf16x8 B = *(const bf16x8*)(qp + 16 * ks);
; #pragma unroll
;       for (int mt = 0; mt < 4; ++mt) sc[mt] = mfma32(*(const LAS bf16x8*)(lds + ((hf * 4 + mt) * 32 + il) * KS + (16 * ks + 8 * h) * 2), B, sc[mt]);
;     }
;     float mx = mxp;
; #pragma unroll
;     for (int mt = 0; mt < 4; ++mt)
; #pragma unroll
;       for (int r = 0; r < 16; ++r) mx = fmaxf(mx, sc[mt][r]);
;     mx = fmaxf(mx, __shfl_xor(mx, 32));
	v_mfma_f32_32x32x16_bf16 v[16:31], v[78:81], v[198:201], v[16:31]
	ds_read_b128 v[78:81], v138 offset:34080
	s_waitcnt lgkmcnt(3)
	v_mfma_f32_32x32x16_bf16 v[0:15], v[82:85], v[198:201], v[0:15]
	ds_read_b128 v[82:85], v138 offset:50976
	s_waitcnt vmcnt(6)
	s_waitcnt lgkmcnt(3)
	v_mfma_f32_32x32x16_bf16 v[48:63], v[70:73], v[202:205], v[48:63]
	ds_read_b128 v[70:73], v138 offset:320
	s_waitcnt lgkmcnt(3)
	v_mfma_f32_32x32x16_bf16 v[32:47], v[74:77], v[202:205], v[32:47]
	ds_read_b128 v[74:77], v138 offset:17216
	s_waitcnt lgkmcnt(3)
	v_mfma_f32_32x32x16_bf16 v[16:31], v[78:81], v[202:205], v[16:31]
	ds_read_b128 v[78:81], v138 offset:34112
	s_waitcnt lgkmcnt(3)
	v_mfma_f32_32x32x16_bf16 v[0:15], v[82:85], v[202:205], v[0:15]
	ds_read_b128 v[82:85], v138 offset:51008
	s_waitcnt vmcnt(5)
	s_waitcnt lgkmcnt(3)
	v_mfma_f32_32x32x16_bf16 v[48:63], v[70:73], v[206:209], v[48:63]
	ds_read_b128 v[70:73], v138 offset:352
	s_waitcnt lgkmcnt(3)
	v_mfma_f32_32x32x16_bf16 v[32:47], v[74:77], v[206:209], v[32:47]
	ds_read_b128 v[74:77], v138 offset:17248
	s_waitcnt lgkmcnt(3)
	v_mfma_f32_32x32x16_bf16 v[16:31], v[78:81], v[206:209], v[16:31]
	ds_read_b128 v[78:81], v138 offset:34144
	s_waitcnt lgkmcnt(3)
	v_mfma_f32_32x32x16_bf16 v[0:15], v[82:85], v[206:209], v[0:15]
	ds_read_b128 v[82:85], v138 offset:51040
	s_waitcnt vmcnt(4)
	s_waitcnt lgkmcnt(3)
	v_mfma_f32_32x32x16_bf16 v[48:63], v[70:73], v[226:229], v[48:63]
	ds_read_b128 v[70:73], v138 offset:384
	s_waitcnt lgkmcnt(3)
	v_mfma_f32_32x32x16_bf16 v[32:47], v[74:77], v[226:229], v[32:47]
	ds_read_b128 v[74:77], v138 offset:17280
	s_waitcnt lgkmcnt(3)
	v_mfma_f32_32x32x16_bf16 v[16:31], v[78:81], v[226:229], v[16:31]
	ds_read_b128 v[78:81], v138 offset:34176
	s_waitcnt lgkmcnt(3)
	v_mfma_f32_32x32x16_bf16 v[0:15], v[82:85], v[226:229], v[0:15]
	ds_read_b128 v[82:85], v138 offset:51072
	s_waitcnt vmcnt(3)
	s_waitcnt lgkmcnt(3)
	v_mfma_f32_32x32x16_bf16 v[48:63], v[70:73], v[232:235], v[48:63]
	ds_read_b128 v[70:73], v138 offset:416
	s_waitcnt lgkmcnt(3)
	v_mfma_f32_32x32x16_bf16 v[32:47], v[74:77], v[232:235], v[32:47]
	ds_read_b128 v[74:77], v138 offset:17312
	s_waitcnt lgkmcnt(3)
	v_mfma_f32_32x32x16_bf16 v[16:31], v[78:81], v[232:235], v[16:31]
	ds_read_b128 v[78:81], v138 offset:34208
	s_waitcnt lgkmcnt(3)
	v_mfma_f32_32x32x16_bf16 v[0:15], v[82:85], v[232:235], v[0:15]
	ds_read_b128 v[82:85], v138 offset:51104
	s_waitcnt vmcnt(2)
	s_waitcnt lgkmcnt(3)
	v_mfma_f32_32x32x16_bf16 v[48:63], v[70:73], v[236:239], v[48:63]
	ds_read_b128 v[70:73], v138 offset:448
	s_waitcnt lgkmcnt(3)
	v_mfma_f32_32x32x16_bf16 v[32:47], v[74:77], v[236:239], v[32:47]
	ds_read_b128 v[74:77], v138 offset:17344
	s_waitcnt lgkmcnt(3)
	v_mfma_f32_32x32x16_bf16 v[16:31], v[78:81], v[236:239], v[16:31]
	ds_read_b128 v[78:81], v138 offset:34240
	s_waitcnt lgkmcnt(3)
	v_mfma_f32_32x32x16_bf16 v[0:15], v[82:85], v[236:239], v[0:15]
	ds_read_b128 v[82:85], v138 offset:51136
	s_waitcnt vmcnt(1)
	s_waitcnt lgkmcnt(3)
	v_mfma_f32_32x32x16_bf16 v[48:63], v[70:73], v[240:243], v[48:63]
	ds_read_b128 v[70:73], v138 offset:480
	s_waitcnt lgkmcnt(3)
	v_mfma_f32_32x32x16_bf16 v[32:47], v[74:77], v[240:243], v[32:47]
	ds_read_b128 v[74:77], v138 offset:17376
	s_waitcnt lgkmcnt(3)
	v_mfma_f32_32x32x16_bf16 v[16:31], v[78:81], v[240:243], v[16:31]
	ds_read_b128 v[78:81], v138 offset:34272
	s_waitcnt lgkmcnt(3)
	v_mfma_f32_32x32x16_bf16 v[0:15], v[82:85], v[240:243], v[0:15]
	ds_read_b128 v[82:85], v138 offset:51168
	s_waitcnt vmcnt(0)
	s_waitcnt lgkmcnt(3)
	v_mfma_f32_32x32x16_bf16 v[48:63], v[70:73], v[66:69], v[48:63]
	s_waitcnt lgkmcnt(2)
	v_mfma_f32_32x32x16_bf16 v[32:47], v[74:77], v[66:69], v[32:47]
	s_waitcnt lgkmcnt(1)
	v_mfma_f32_32x32x16_bf16 v[16:31], v[78:81], v[66:69], v[16:31]
	s_waitcnt lgkmcnt(0)
	v_mfma_f32_32x32x16_bf16 v[0:15], v[82:85], v[66:69], v[0:15]
	s_movk_i32 s12, 0x200
	v_and_b32_e32 v65, 64, v219
	v_xor_b32_e32 v64, 32, v219
	v_add_u32_e32 v65, 64, v65
	v_cmp_lt_i32_e32 vcc, v64, v65
	s_mov_b32 s13, 0xff61b1e6
	s_mov_b32 s12, 0
	v_cndmask_b32_e32 v64, v219, v64, vcc
	v_lshlrev_b32_e32 v137, 2, v64
	v_max3_f32 v64, v48, s13, v49
	v_max3_f32 v64, v64, v50, v51
	v_max3_f32 v64, v64, v52, v53
	v_max3_f32 v64, v64, v54, v55
	v_max3_f32 v64, v64, v56, v57
	v_max3_f32 v64, v64, v58, v59
	v_max3_f32 v64, v64, v60, v61
	v_max3_f32 v64, v64, v62, v63
	v_max3_f32 v64, v64, v32, v33
	v_max3_f32 v64, v64, v34, v35
	v_max3_f32 v64, v64, v36, v37
	v_max3_f32 v64, v64, v38, v39
	v_max3_f32 v64, v64, v40, v41
	v_max3_f32 v64, v64, v42, v43
	v_max3_f32 v64, v64, v44, v45
	v_max3_f32 v64, v64, v46, v47
	v_max3_f32 v64, v64, v16, v17
	v_max3_f32 v64, v64, v18, v19
	v_max3_f32 v64, v64, v20, v21
	v_max3_f32 v64, v64, v22, v23
	v_max3_f32 v64, v64, v24, v25
	v_max3_f32 v64, v64, v26, v27
	v_max3_f32 v64, v64, v28, v29
	v_max3_f32 v64, v64, v30, v31
	v_max3_f32 v64, v64, v0, v1
	v_max3_f32 v64, v64, v2, v3
	v_max3_f32 v64, v64, v4, v5
	v_max3_f32 v64, v64, v6, v7
	v_max3_f32 v64, v64, v8, v9
	v_max3_f32 v64, v64, v10, v11
	v_max3_f32 v64, v64, v12, v13
	v_max3_f32 v139, v64, v14, v15
	ds_bpermute_b32 v140, v137, v139
	v_mov_b32_e32 v64, 0
	v_mov_b32_e32 v65, v64
	v_mov_b32_e32 v66, v64
	v_mov_b32_e32 v67, v64
	v_mov_b32_e32 v68, v64
	v_mov_b32_e32 v69, v64
	v_mov_b32_e32 v70, v64
	v_mov_b32_e32 v71, v64
	v_mov_b32_e32 v72, v64
	v_mov_b32_e32 v73, v64
	v_mov_b32_e32 v74, v64
	v_mov_b32_e32 v75, v64
	v_mov_b32_e32 v76, v64
	v_mov_b32_e32 v77, v64
	v_mov_b32_e32 v78, v64
	v_mov_b32_e32 v79, v64
	v_mov_b32_e32 v80, v64
	v_mov_b32_e32 v81, v64
	v_mov_b32_e32 v82, v64
	v_mov_b32_e32 v83, v64
	v_mov_b32_e32 v84, v64
	v_mov_b32_e32 v85, v64
	v_mov_b32_e32 v86, v64
	v_mov_b32_e32 v87, v64
	v_mov_b32_e32 v88, v64
	v_mov_b32_e32 v89, v64
	v_mov_b32_e32 v90, v64
	v_mov_b32_e32 v91, v64
	v_mov_b32_e32 v92, v64
	v_mov_b32_e32 v93, v64
	v_mov_b32_e32 v94, v64
	v_mov_b32_e32 v95, v64
	v_mov_b32_e32 v96, v64
	v_mov_b32_e32 v97, v64
	v_mov_b32_e32 v98, v64
	v_mov_b32_e32 v99, v64
	v_mov_b32_e32 v100, v64
	v_mov_b32_e32 v101, v64
	v_mov_b32_e32 v102, v64
	v_mov_b32_e32 v103, v64
	v_mov_b32_e32 v104, v64
	v_mov_b32_e32 v105, v64
	v_mov_b32_e32 v106, v64
	v_mov_b32_e32 v107, v64
	v_mov_b32_e32 v108, v64
	v_mov_b32_e32 v109, v64
	v_mov_b32_e32 v110, v64
	v_mov_b32_e32 v111, v64
	v_mov_b32_e32 v112, v64
	v_mov_b32_e32 v113, v64
	v_mov_b32_e32 v114, v64
	v_mov_b32_e32 v115, v64
	v_mov_b32_e32 v116, v64
	v_mov_b32_e32 v117, v64
	v_mov_b32_e32 v118, v64
	v_mov_b32_e32 v119, v64
	v_mov_b32_e32 v120, v64
	v_mov_b32_e32 v121, v64
	v_mov_b32_e32 v122, v64
	v_mov_b32_e32 v123, v64
	v_mov_b32_e32 v124, v64
	v_mov_b32_e32 v125, v64
	v_mov_b32_e32 v126, v64
	v_mov_b32_e32 v127, v64
	v_add_u32_e32 v141, 0x10800, v138
	global_load_dwordx4 v[142:145], v[134:135], off offset:416
	ds_read_b128 v[146:149], v141 offset:0
	s_waitcnt vmcnt(1)
; #define LAS __attribute__((address_space(3)))
; __device__ __forceinline__ f32x16 mfma32(bf16x8 a, bf16x8 b, f32x16 c) { return __builtin_amdgcn_mfma_f32_32x32x16_bf16(a, b, c, 0, 0, 0); }
; __device__ void attn_item(const bf16_t* __restrict__ QX, const bf16_t* __restrict__ KV, bf16_t* __restrict__ O, int tt, int head, LAS unsigned char* lds) {
;     ...
;     for (int ks = 0; ks < 16; ++ks) {
;       const bf16x8 B = *(const bf16x8*)(qp + 16 * ks);
; #pragma unroll
;       for (int mt = 0; mt < 4; ++mt) sc[mt] = mfma32(*(const LAS bf16x8*)(lds + ((hf * 4 + mt) * 32 + il) * KS + (16 * ks + 8 * h) * 2), B, sc[mt]);
	s_waitcnt lgkmcnt(0)
	v_mfma_f32_32x32x16_bf16 v[112:127], v[146:149], v[150:153], v[112:127]
	ds_read_b128 v[146:149], v141 offset:16896
	s_waitcnt lgkmcnt(0)
	v_mfma_f32_32x32x16_bf16 v[96:111], v[146:149], v[150:153], v[96:111]
	ds_read_b128 v[146:149], v141 offset:33792
	s_waitcnt lgkmcnt(0)
	v_mfma_f32_32x32x16_bf16 v[80:95], v[146:149], v[150:153], v[80:95]
	ds_read_b128 v[146:149], v141 offset:50688
	s_waitcnt lgkmcnt(0)
	v_mfma_f32_32x32x16_bf16 v[64:79], v[146:149], v[150:153], v[64:79]
	ds_read_b128 v[146:149], v141 offset:32
	s_waitcnt vmcnt(1)
	s_waitcnt lgkmcnt(0)
	v_mfma_f32_32x32x16_bf16 v[112:127], v[146:149], v[154:157], v[112:127]
	ds_read_b128 v[146:149], v141 offset:16928
	s_waitcnt lgkmcnt(0)
	v_mfma_f32_32x32x16_bf16 v[96:111], v[146:149], v[154:157], v[96:111]
	ds_read_b128 v[146:149], v141 offset:33824
	s_waitcnt lgkmcnt(0)
	v_mfma_f32_32x32x16_bf16 v[80:95], v[146:149], v[154:157], v[80:95]
	ds_read_b128 v[146:149], v141 offset:50720
	s_waitcnt lgkmcnt(0)
	v_mfma_f32_32x32x16_bf16 v[64:79], v[146:149], v[154:157], v[64:79]
	ds_read_b128 v[146:149], v141 offset:64
	s_waitcnt vmcnt(1)
	s_waitcnt lgkmcnt(0)
	v_mfma_f32_32x32x16_bf16 v[112:127], v[146:149], v[174:177], v[112:127]
	ds_read_b128 v[146:149], v141 offset:16960
	s_waitcnt lgkmcnt(0)
	v_mfma_f32_32x32x16_bf16 v[96:111], v[146:149], v[174:177], v[96:111]
	ds_read_b128 v[146:149], v141 offset:33856
	s_waitcnt lgkmcnt(0)
	v_mfma_f32_32x32x16_bf16 v[80:95], v[146:149], v[174:177], v[80:95]
	ds_read_b128 v[146:149], v141 offset:50752
	s_waitcnt lgkmcnt(0)
	v_mfma_f32_32x32x16_bf16 v[64:79], v[146:149], v[174:177], v[64:79]
	ds_read_b128 v[146:149], v141 offset:96
	s_waitcnt vmcnt(1)
	s_waitcnt lgkmcnt(0)
	v_mfma_f32_32x32x16_bf16 v[112:127], v[146:149], v[178:181], v[112:127]
	ds_read_b128 v[146:149], v141 offset:16992
	s_waitcnt lgkmcnt(0)
	v_mfma_f32_32x32x16_bf16 v[96:111], v[146:149], v[178:181], v[96:111]
	ds_read_b128 v[146:149], v141 offset:33888
	s_waitcnt lgkmcnt(0)
	v_mfma_f32_32x32x16_bf16 v[80:95], v[146:149], v[178:181], v[80:95]
	ds_read_b128 v[146:149], v141 offset:50784
	s_waitcnt lgkmcnt(0)
	v_mfma_f32_32x32x16_bf16 v[64:79], v[146:149], v[178:181], v[64:79]
	ds_read_b128 v[146:149], v141 offset:128
	s_waitcnt vmcnt(1)
	s_waitcnt lgkmcnt(0)
	v_mfma_f32_32x32x16_bf16 v[112:127], v[146:149], v[182:185], v[112:127]
	ds_read_b128 v[146:149], v141 offset:17024
	s_waitcnt lgkmcnt(0)
	v_mfma_f32_32x32x16_bf16 v[96:111], v[146:149], v[182:185], v[96:111]
	ds_read_b128 v[146:149], v141 offset:33920
	s_waitcnt lgkmcnt(0)
	v_mfma_f32_32x32x16_bf16 v[80:95], v[146:149], v[182:185], v[80:95]
	ds_read_b128 v[146:149], v141 offset:50816
	s_waitcnt lgkmcnt(0)
	v_mfma_f32_32x32x16_bf16 v[64:79], v[146:149], v[182:185], v[64:79]
	ds_read_b128 v[146:149], v141 offset:160
	s_waitcnt vmcnt(1)
	s_waitcnt lgkmcnt(0)
	v_mfma_f32_32x32x16_bf16 v[112:127], v[146:149], v[186:189], v[112:127]
	ds_read_b128 v[146:149], v141 offset:17056
	s_waitcnt lgkmcnt(0)
	v_mfma_f32_32x32x16_bf16 v[96:111], v[146:149], v[186:189], v[96:111]
	ds_read_b128 v[146:149], v141 offset:33952
	s_waitcnt lgkmcnt(0)
	v_mfma_f32_32x32x16_bf16 v[80:95], v[146:149], v[186:189], v[80:95]
	ds_read_b128 v[146:149], v141 offset:50848
	s_waitcnt lgkmcnt(0)
	v_mfma_f32_32x32x16_bf16 v[64:79], v[146:149], v[186:189], v[64:79]
	ds_read_b128 v[146:149], v141 offset:192
	s_waitcnt vmcnt(1)
	s_waitcnt lgkmcnt(0)
	v_mfma_f32_32x32x16_bf16 v[112:127], v[146:149], v[190:193], v[112:127]
	ds_read_b128 v[146:149], v141 offset:17088
	s_waitcnt lgkmcnt(0)
	v_mfma_f32_32x32x16_bf16 v[96:111], v[146:149], v[190:193], v[96:111]
	ds_read_b128 v[146:149], v141 offset:33984
	s_waitcnt lgkmcnt(0)
	v_mfma_f32_32x32x16_bf16 v[80:95], v[146:149], v[190:193], v[80:95]
	ds_read_b128 v[146:149], v141 offset:50880
	s_waitcnt lgkmcnt(0)
	v_mfma_f32_32x32x16_bf16 v[64:79], v[146:149], v[190:193], v[64:79]
	ds_read_b128 v[146:149], v141 offset:224
	s_waitcnt vmcnt(1)
	s_waitcnt lgkmcnt(0)
	v_mfma_f32_32x32x16_bf16 v[112:127], v[146:149], v[194:197], v[112:127]
	ds_read_b128 v[146:149], v141 offset:17120
	s_waitcnt lgkmcnt(0)
	v_mfma_f32_32x32x16_bf16 v[96:111], v[146:149], v[194:197], v[96:111]
	ds_read_b128 v[146:149], v141 offset:34016
	s_waitcnt lgkmcnt(0)
	v_mfma_f32_32x32x16_bf16 v[80:95], v[146:149], v[194:197], v[80:95]
	ds_read_b128 v[146:149], v141 offset:50912
	s_waitcnt lgkmcnt(0)
	v_mfma_f32_32x32x16_bf16 v[64:79], v[146:149], v[194:197], v[64:79]
	ds_read_b128 v[146:149], v141 offset:256
	s_waitcnt vmcnt(1)
	s_waitcnt lgkmcnt(0)
	v_mfma_f32_32x32x16_bf16 v[112:127], v[146:149], v[198:201], v[112:127]
	ds_read_b128 v[146:149], v141 offset:17152
	s_waitcnt lgkmcnt(0)
	v_mfma_f32_32x32x16_bf16 v[96:111], v[146:149], v[198:201], v[96:111]
	ds_read_b128 v[146:149], v141 offset:34048
	s_waitcnt lgkmcnt(0)
	v_mfma_f32_32x32x16_bf16 v[80:95], v[146:149], v[198:201], v[80:95]
	ds_read_b128 v[146:149], v141 offset:50944
	s_waitcnt lgkmcnt(0)
	v_mfma_f32_32x32x16_bf16 v[64:79], v[146:149], v[198:201], v[64:79]
	ds_read_b128 v[146:149], v141 offset:288
	s_waitcnt vmcnt(1)
	s_waitcnt lgkmcnt(0)
	v_mfma_f32_32x32x16_bf16 v[112:127], v[146:149], v[202:205], v[112:127]
	ds_read_b128 v[146:149], v141 offset:17184
	s_waitcnt lgkmcnt(0)
	v_mfma_f32_32x32x16_bf16 v[96:111], v[146:149], v[202:205], v[96:111]
	ds_read_b128 v[146:149], v141 offset:34080
	s_waitcnt lgkmcnt(0)
	v_mfma_f32_32x32x16_bf16 v[80:95], v[146:149], v[202:205], v[80:95]
	ds_read_b128 v[146:149], v141 offset:50976
	s_waitcnt lgkmcnt(0)
	v_mfma_f32_32x32x16_bf16 v[64:79], v[146:149], v[202:205], v[64:79]
	ds_read_b128 v[146:149], v141 offset:320
	s_waitcnt vmcnt(1)
; #define LAS __attribute__((address_space(3)))
; __device__ __forceinline__ unsigned cvt_pk_bf16(float lo, float hi) { f32x2 v = {lo, hi}; bf16x2_t b = __builtin_convertvector(v, bf16x2_t); return __builtin_bit_cast(unsigned, b); }
; __device__ __forceinline__ f32x16 mfma32(bf16x8 a, bf16x8 b, f32x16 c) { return __builtin_amdgcn_mfma_f32_32x32x16_bf16(a, b, c, 0, 0, 0); }
; __device__ void attn_item(const bf16_t* __restrict__ QX, const bf16_t* __restrict__ KV, bf16_t* __restrict__ O, int tt, int head, LAS unsigned char* lds) {
;     ...
;       for (int mt = 0; mt < 4; ++mt) sc[mt] = mfma32(*(const LAS bf16x8*)(lds + ((hf * 4 + mt) * 32 + il) * KS + (16 * ks + 8 * h) * 2), B, sc[mt]);
;     }
;     float mx = mxp;
; #pragma unroll
;     for (int mt = 0; mt < 4; ++mt)
; #pragma unroll
;       for (int r = 0; r < 16; ++r) mx = fmaxf(mx, sc[mt][r]);
;     mx = fmaxf(mx, __shfl_xor(mx, 32));
;     if (hf == 1) { const float f = __builtin_amdgcn_exp2f((mxp - mx) * 1.4426950408889634f); sum *= f;
; #pragma unroll
;       for (int mt = 0; mt < 4; ++mt) { pf[mt][0] = scale_frag(pf[mt][0], f); pf[mt][1] = scale_frag(pf[mt][1], f); } }
; #pragma unroll
;     for (int mt = 0; mt < 4; ++mt) {
;       u32x4 p0, p1;
; #pragma unroll
;       for (int r = 0; r < 16; r += 2) {
;         const float e0 = __builtin_amdgcn_exp2f((sc[mt][r] - mx) * 1.4426950408889634f), e1 = __builtin_amdgcn_exp2f((sc[mt][r + 1] - mx) * 1.4426950408889634f);
;         sum += e0 + e1; const unsigned pk = cvt_pk_bf16(e0, e1);
	s_waitcnt lgkmcnt(0)
	v_mfma_f32_32x32x16_bf16 v[112:127], v[146:149], v[206:209], v[112:127]
	ds_read_b128 v[146:149], v141 offset:17216
	s_waitcnt lgkmcnt(0)
	v_mfma_f32_32x32x16_bf16 v[96:111], v[146:149], v[206:209], v[96:111]
	ds_read_b128 v[146:149], v141 offset:34112
	s_waitcnt lgkmcnt(0)
	v_mfma_f32_32x32x16_bf16 v[80:95], v[146:149], v[206:209], v[80:95]
	ds_read_b128 v[146:149], v141 offset:51008
	s_waitcnt lgkmcnt(0)
	v_mfma_f32_32x32x16_bf16 v[64:79], v[146:149], v[206:209], v[64:79]
	ds_read_b128 v[146:149], v141 offset:352
	s_waitcnt vmcnt(1)
	s_waitcnt lgkmcnt(0)
	v_mfma_f32_32x32x16_bf16 v[112:127], v[146:149], v[226:229], v[112:127]
	ds_read_b128 v[146:149], v141 offset:17248
	s_waitcnt lgkmcnt(0)
	v_mfma_f32_32x32x16_bf16 v[96:111], v[146:149], v[226:229], v[96:111]
	ds_read_b128 v[146:149], v141 offset:34144
	s_waitcnt lgkmcnt(0)
	v_mfma_f32_32x32x16_bf16 v[80:95], v[146:149], v[226:229], v[80:95]
	ds_read_b128 v[146:149], v141 offset:51040
	s_waitcnt lgkmcnt(0)
	v_mfma_f32_32x32x16_bf16 v[64:79], v[146:149], v[226:229], v[64:79]
	ds_read_b128 v[146:149], v141 offset:384
	s_waitcnt vmcnt(1)
	s_waitcnt lgkmcnt(0)
	v_mfma_f32_32x32x16_bf16 v[112:127], v[146:149], v[232:235], v[112:127]
	ds_read_b128 v[146:149], v141 offset:17280
	s_waitcnt lgkmcnt(0)
	v_mfma_f32_32x32x16_bf16 v[96:111], v[146:149], v[232:235], v[96:111]
	ds_read_b128 v[146:149], v141 offset:34176
	s_waitcnt lgkmcnt(0)
	v_mfma_f32_32x32x16_bf16 v[80:95], v[146:149], v[232:235], v[80:95]
	ds_read_b128 v[146:149], v141 offset:51072
	s_waitcnt lgkmcnt(0)
	v_mfma_f32_32x32x16_bf16 v[64:79], v[146:149], v[232:235], v[64:79]
	ds_read_b128 v[146:149], v141 offset:416
	s_waitcnt vmcnt(1)
	s_waitcnt lgkmcnt(0)
	v_mfma_f32_32x32x16_bf16 v[112:127], v[146:149], v[236:239], v[112:127]
	ds_read_b128 v[146:149], v141 offset:17312
	s_waitcnt lgkmcnt(0)
	v_mfma_f32_32x32x16_bf16 v[96:111], v[146:149], v[236:239], v[96:111]
	ds_read_b128 v[146:149], v141 offset:34208
	s_waitcnt lgkmcnt(0)
	v_mfma_f32_32x32x16_bf16 v[80:95], v[146:149], v[236:239], v[80:95]
	ds_read_b128 v[146:149], v141 offset:51104
	s_waitcnt lgkmcnt(0)
	v_mfma_f32_32x32x16_bf16 v[64:79], v[146:149], v[236:239], v[64:79]
	ds_read_b128 v[146:149], v141 offset:448
	s_waitcnt vmcnt(1)
	s_waitcnt lgkmcnt(0)
	v_mfma_f32_32x32x16_bf16 v[112:127], v[146:149], v[240:243], v[112:127]
	ds_read_b128 v[146:149], v141 offset:17344
	s_waitcnt lgkmcnt(0)
	v_mfma_f32_32x32x16_bf16 v[96:111], v[146:149], v[240:243], v[96:111]
	ds_read_b128 v[146:149], v141 offset:34240
	s_waitcnt lgkmcnt(0)
	v_mfma_f32_32x32x16_bf16 v[80:95], v[146:149], v[240:243], v[80:95]
	ds_read_b128 v[146:149], v141 offset:51136
	s_waitcnt lgkmcnt(0)
	v_mfma_f32_32x32x16_bf16 v[64:79], v[146:149], v[240:243], v[64:79]
	ds_read_b128 v[146:149], v141 offset:480
	s_waitcnt vmcnt(0)
	s_waitcnt lgkmcnt(0)
	v_mfma_f32_32x32x16_bf16 v[112:127], v[146:149], v[142:145], v[112:127]
	ds_read_b128 v[146:149], v141 offset:17376
	s_waitcnt lgkmcnt(0)
	v_mfma_f32_32x32x16_bf16 v[96:111], v[146:149], v[142:145], v[96:111]
	ds_read_b128 v[146:149], v141 offset:34272
	s_waitcnt lgkmcnt(0)
	v_mfma_f32_32x32x16_bf16 v[80:95], v[146:149], v[142:145], v[80:95]
	ds_read_b128 v[146:149], v141 offset:51168
	s_waitcnt lgkmcnt(0)
	v_mfma_f32_32x32x16_bf16 v[64:79], v[146:149], v[142:145], v[64:79]
	s_movk_i32 s12, 0x200
	v_max_f32_e32 v134, v140, v140
	v_max_f32_e32 v135, v139, v139
	v_max_f32_e32 v152, v135, v134
	v_sub_f32_e32 v0, v0, v152
	v_sub_f32_e32 v48, v48, v152
	v_sub_f32_e32 v49, v49, v152
	v_mul_f32_e32 v0, 0x3fb8aa3b, v0
	v_mul_f32_e32 v48, 0x3fb8aa3b, v48
	v_mul_f32_e32 v49, 0x3fb8aa3b, v49
	v_sub_f32_e32 v50, v50, v152
	v_sub_f32_e32 v51, v51, v152
	v_exp_f32_e32 v134, v0
	v_sub_f32_e32 v0, v1, v152
	v_exp_f32_e32 v48, v48
	v_exp_f32_e32 v49, v49
	v_mul_f32_e32 v50, 0x3fb8aa3b, v50
	v_mul_f32_e32 v51, 0x3fb8aa3b, v51
	v_sub_f32_e32 v52, v52, v152
	v_sub_f32_e32 v53, v53, v152
	v_mul_f32_e32 v0, 0x3fb8aa3b, v0
	v_exp_f32_e32 v50, v50
	v_exp_f32_e32 v51, v51
	v_mul_f32_e32 v52, 0x3fb8aa3b, v52
	v_mul_f32_e32 v53, 0x3fb8aa3b, v53
	v_sub_f32_e32 v54, v54, v152
	v_sub_f32_e32 v55, v55, v152
	v_exp_f32_e32 v135, v0
	v_sub_f32_e32 v0, v2, v152
	v_exp_f32_e32 v52, v52
	v_exp_f32_e32 v53, v53
	v_mul_f32_e32 v54, 0x3fb8aa3b, v54
	v_mul_f32_e32 v55, 0x3fb8aa3b, v55
	v_sub_f32_e32 v56, v56, v152
	v_sub_f32_e32 v57, v57, v152
	v_mul_f32_e32 v0, 0x3fb8aa3b, v0
	v_exp_f32_e32 v54, v54
	v_exp_f32_e32 v55, v55
	v_mul_f32_e32 v56, 0x3fb8aa3b, v56
	v_mul_f32_e32 v57, 0x3fb8aa3b, v57
	v_sub_f32_e32 v58, v58, v152
	v_sub_f32_e32 v59, v59, v152
	v_exp_f32_e32 v138, v0
	v_sub_f32_e32 v0, v3, v152
	v_add_f32_e32 v153, v48, v49
	v_exp_f32_e32 v56, v56
	v_exp_f32_e32 v57, v57
	v_mul_f32_e32 v58, 0x3fb8aa3b, v58
	v_mul_f32_e32 v59, 0x3fb8aa3b, v59
	v_sub_f32_e32 v60, v60, v152
	v_sub_f32_e32 v61, v61, v152
	v_mul_f32_e32 v0, 0x3fb8aa3b, v0
	v_add_f32_e32 v154, v50, v51
	v_exp_f32_e32 v58, v58
	v_exp_f32_e32 v59, v59
	v_mul_f32_e32 v60, 0x3fb8aa3b, v60
	v_mul_f32_e32 v61, 0x3fb8aa3b, v61
	v_sub_f32_e32 v62, v62, v152
	v_sub_f32_e32 v63, v63, v152
	v_exp_f32_e32 v139, v0
	v_sub_f32_e32 v0, v4, v152
	v_sub_f32_e32 v4, v8, v152
	v_add_f32_e32 v8, 0, v153
	v_add_f32_e32 v155, v52, v53
	v_exp_f32_e32 v60, v60
	v_exp_f32_e32 v61, v61
	v_mul_f32_e32 v62, 0x3fb8aa3b, v62
	v_mul_f32_e32 v63, 0x3fb8aa3b, v63
	v_sub_f32_e32 v32, v32, v152
	v_sub_f32_e32 v33, v33, v152
	v_add_f32_e32 v8, v154, v8
	v_add_f32_e32 v156, v54, v55
	v_exp_f32_e32 v62, v62
	v_exp_f32_e32 v63, v63
	v_mul_f32_e32 v32, 0x3fb8aa3b, v32
	v_mul_f32_e32 v33, 0x3fb8aa3b, v33
	v_sub_f32_e32 v34, v34, v152
	v_sub_f32_e32 v35, v35, v152
; __device__ __forceinline__ unsigned cvt_pk_bf16(float lo, float hi) { f32x2 v = {lo, hi}; bf16x2_t b = __builtin_convertvector(v, bf16x2_t); return __builtin_bit_cast(unsigned, b); }
; __device__ void attn_item(const bf16_t* __restrict__ QX, const bf16_t* __restrict__ KV, bf16_t* __restrict__ O, int tt, int head, LAS unsigned char* lds) {
;     ...
;     float mx = mxp;
; #pragma unroll
;     for (int mt = 0; mt < 4; ++mt)
; #pragma unroll
;       for (int r = 0; r < 16; ++r) mx = fmaxf(mx, sc[mt][r]);
;     mx = fmaxf(mx, __shfl_xor(mx, 32));
;     if (hf == 1) { const float f = __builtin_amdgcn_exp2f((mxp - mx) * 1.4426950408889634f); sum *= f;
; #pragma unroll
;       for (int mt = 0; mt < 4; ++mt) { pf[mt][0] = scale_frag(pf[mt][0], f); pf[mt][1] = scale_frag(pf[mt][1], f); } }
; #pragma unroll
;     for (int mt = 0; mt < 4; ++mt) {
;       u32x4 p0, p1;
; #pragma unroll
;       for (int r = 0; r < 16; r += 2) {
;         const float e0 = __builtin_amdgcn_exp2f((sc[mt][r] - mx) * 1.4426950408889634f), e1 = __builtin_amdgcn_exp2f((sc[mt][r + 1] - mx) * 1.4426950408889634f);
;         sum += e0 + e1; const unsigned pk = cvt_pk_bf16(e0, e1);
	v_add_f32_e32 v8, v155, v8
	v_add_f32_e32 v157, v56, v57
	v_exp_f32_e32 v32, v32
	v_exp_f32_e32 v33, v33
	v_mul_f32_e32 v34, 0x3fb8aa3b, v34
	v_mul_f32_e32 v35, 0x3fb8aa3b, v35
	v_sub_f32_e32 v36, v36, v152
	v_sub_f32_e32 v37, v37, v152
	v_add_f32_e32 v8, v156, v8
	v_add_f32_e32 v158, v58, v59
	v_exp_f32_e32 v34, v34
	v_exp_f32_e32 v35, v35
	v_mul_f32_e32 v36, 0x3fb8aa3b, v36
	v_mul_f32_e32 v37, 0x3fb8aa3b, v37
	v_sub_f32_e32 v38, v38, v152
	v_sub_f32_e32 v39, v39, v152
	v_add_f32_e32 v8, v157, v8
	v_add_f32_e32 v159, v60, v61
	v_exp_f32_e32 v36, v36
	v_exp_f32_e32 v37, v37
	v_mul_f32_e32 v38, 0x3fb8aa3b, v38
	v_mul_f32_e32 v39, 0x3fb8aa3b, v39
	v_sub_f32_e32 v40, v40, v152
	v_sub_f32_e32 v41, v41, v152
	v_add_f32_e32 v8, v158, v8
	v_add_f32_e32 v174, v62, v63
	v_exp_f32_e32 v38, v38
	v_exp_f32_e32 v39, v39
	v_mul_f32_e32 v40, 0x3fb8aa3b, v40
	v_mul_f32_e32 v41, 0x3fb8aa3b, v41
	v_sub_f32_e32 v42, v42, v152
	v_sub_f32_e32 v43, v43, v152
	v_add_f32_e32 v8, v159, v8
	v_add_f32_e32 v175, v32, v33
	v_exp_f32_e32 v40, v40
	v_exp_f32_e32 v41, v41
	v_mul_f32_e32 v42, 0x3fb8aa3b, v42
	v_mul_f32_e32 v43, 0x3fb8aa3b, v43
	v_sub_f32_e32 v44, v44, v152
	v_sub_f32_e32 v45, v45, v152
	v_add_f32_e32 v8, v174, v8
	v_add_f32_e32 v176, v34, v35
	v_exp_f32_e32 v42, v42
	v_exp_f32_e32 v43, v43
	v_mul_f32_e32 v44, 0x3fb8aa3b, v44
	v_mul_f32_e32 v45, 0x3fb8aa3b, v45
	v_sub_f32_e32 v46, v46, v152
	v_sub_f32_e32 v47, v47, v152
	v_add_f32_e32 v8, v175, v8
	v_add_f32_e32 v177, v36, v37
	v_exp_f32_e32 v44, v44
	v_exp_f32_e32 v45, v45
	v_mul_f32_e32 v46, 0x3fb8aa3b, v46
	v_mul_f32_e32 v47, 0x3fb8aa3b, v47
	v_sub_f32_e32 v16, v16, v152
	v_sub_f32_e32 v17, v17, v152
	v_add_f32_e32 v8, v176, v8
	v_add_f32_e32 v178, v38, v39
	v_exp_f32_e32 v46, v46
	v_exp_f32_e32 v47, v47
	v_mul_f32_e32 v16, 0x3fb8aa3b, v16
	v_mul_f32_e32 v17, 0x3fb8aa3b, v17
	v_sub_f32_e32 v18, v18, v152
	v_sub_f32_e32 v19, v19, v152
	v_add_f32_e32 v8, v177, v8
	v_add_f32_e32 v179, v40, v41
	v_exp_f32_e32 v16, v16
	v_exp_f32_e32 v17, v17
	v_mul_f32_e32 v18, 0x3fb8aa3b, v18
	v_mul_f32_e32 v19, 0x3fb8aa3b, v19
	v_sub_f32_e32 v20, v20, v152
	v_sub_f32_e32 v21, v21, v152
	v_add_f32_e32 v8, v178, v8
	v_add_f32_e32 v180, v42, v43
	v_exp_f32_e32 v18, v18
	v_exp_f32_e32 v19, v19
	v_mul_f32_e32 v20, 0x3fb8aa3b, v20
	v_mul_f32_e32 v21, 0x3fb8aa3b, v21
	v_sub_f32_e32 v22, v22, v152
	v_sub_f32_e32 v23, v23, v152
	v_add_f32_e32 v8, v179, v8
	v_add_f32_e32 v181, v44, v45
	v_exp_f32_e32 v20, v20
	v_exp_f32_e32 v21, v21
	v_mul_f32_e32 v22, 0x3fb8aa3b, v22
	v_mul_f32_e32 v23, 0x3fb8aa3b, v23
	v_sub_f32_e32 v24, v24, v152
	v_sub_f32_e32 v25, v25, v152
	v_add_f32_e32 v8, v180, v8
	v_add_f32_e32 v182, v46, v47
	v_exp_f32_e32 v22, v22
	v_exp_f32_e32 v23, v23
	v_mul_f32_e32 v24, 0x3fb8aa3b, v24
	v_mul_f32_e32 v25, 0x3fb8aa3b, v25
	v_sub_f32_e32 v26, v26, v152
	v_sub_f32_e32 v27, v27, v152
	v_add_f32_e32 v8, v181, v8
	v_add_f32_e32 v183, v16, v17
	v_exp_f32_e32 v24, v24
	v_exp_f32_e32 v25, v25
	v_mul_f32_e32 v26, 0x3fb8aa3b, v26
	v_mul_f32_e32 v27, 0x3fb8aa3b, v27
	v_sub_f32_e32 v28, v28, v152
	v_sub_f32_e32 v29, v29, v152
	v_add_f32_e32 v8, v182, v8
	v_add_f32_e32 v184, v18, v19
	v_exp_f32_e32 v26, v26
	v_exp_f32_e32 v27, v27
	v_mul_f32_e32 v28, 0x3fb8aa3b, v28
	v_mul_f32_e32 v29, 0x3fb8aa3b, v29
	v_sub_f32_e32 v30, v30, v152
	v_sub_f32_e32 v31, v31, v152
	v_mul_f32_e32 v0, 0x3fb8aa3b, v0
	v_add_f32_e32 v8, v183, v8
	v_add_f32_e32 v185, v20, v21
	v_exp_f32_e32 v28, v28
	v_exp_f32_e32 v29, v29
	v_mul_f32_e32 v30, 0x3fb8aa3b, v30
	v_mul_f32_e32 v31, 0x3fb8aa3b, v31
	v_exp_f32_e32 v140, v0
	v_sub_f32_e32 v0, v5, v152
	v_add_f32_e32 v8, v184, v8
	v_add_f32_e32 v186, v22, v23
	v_exp_f32_e32 v30, v30
	v_exp_f32_e32 v31, v31
	v_mul_f32_e32 v0, 0x3fb8aa3b, v0
	v_add_f32_e32 v8, v185, v8
	v_add_f32_e32 v187, v24, v25
	v_exp_f32_e32 v141, v0
	v_sub_f32_e32 v0, v6, v152
	v_add_f32_e32 v8, v186, v8
	v_add_f32_e32 v188, v26, v27
	v_mul_f32_e32 v0, 0x3fb8aa3b, v0
	v_add_f32_e32 v8, v187, v8
	v_add_f32_e32 v189, v28, v29
	v_exp_f32_e32 v142, v0
	v_sub_f32_e32 v0, v7, v152
	v_add_f32_e32 v8, v188, v8
	v_add_f32_e32 v190, v30, v31
	v_mul_f32_e32 v0, 0x3fb8aa3b, v0
	v_add_f32_e32 v8, v189, v8
	v_exp_f32_e32 v143, v0
	v_add_f32_e32 v0, v134, v135
	v_add_f32_e32 v8, v190, v8
	v_add_f32_e32 v1, v138, v139
	v_add_f32_e32 v0, v0, v8
	v_add_f32_e32 v0, v1, v0
	v_max3_f32 v1, v152, v112, v113
	v_max3_f32 v1, v1, v114, v115
	v_max3_f32 v1, v1, v116, v117
	v_max3_f32 v1, v1, v118, v119
	v_max3_f32 v1, v1, v120, v121
	v_max3_f32 v1, v1, v122, v123
	v_max3_f32 v1, v1, v124, v125
	v_max3_f32 v1, v1, v126, v127
	v_max3_f32 v1, v1, v96, v97
	v_max3_f32 v1, v1, v98, v99
	v_max3_f32 v1, v1, v100, v101
	v_max3_f32 v1, v1, v102, v103
	v_max3_f32 v1, v1, v104, v105
	v_max3_f32 v1, v1, v106, v107
	v_max3_f32 v1, v1, v108, v109
	v_max3_f32 v1, v1, v110, v111
	v_max3_f32 v1, v1, v80, v81
	v_max3_f32 v1, v1, v82, v83
	v_max3_f32 v1, v1, v84, v85
	v_mul_f32_e32 v4, 0x3fb8aa3b, v4
	v_max3_f32 v1, v1, v86, v87
	v_exp_f32_e32 v144, v4
	v_sub_f32_e32 v4, v9, v152
	v_max3_f32 v1, v1, v88, v89
	v_mul_f32_e32 v4, 0x3fb8aa3b, v4
	v_max3_f32 v1, v1, v90, v91
	v_exp_f32_e32 v145, v4
	v_sub_f32_e32 v4, v10, v152
	v_max3_f32 v1, v1, v92, v93
	v_mul_f32_e32 v4, 0x3fb8aa3b, v4
	v_max3_f32 v1, v1, v94, v95
	v_exp_f32_e32 v146, v4
	v_sub_f32_e32 v4, v11, v152
	v_max3_f32 v1, v1, v64, v65
	v_mul_f32_e32 v4, 0x3fb8aa3b, v4
	v_max3_f32 v1, v1, v66, v67
	v_exp_f32_e32 v147, v4
	v_sub_f32_e32 v4, v12, v152
	v_max3_f32 v1, v1, v68, v69
	v_mul_f32_e32 v4, 0x3fb8aa3b, v4
	v_max3_f32 v1, v1, v70, v71
	v_exp_f32_e32 v148, v4
	v_sub_f32_e32 v4, v13, v152
	v_max3_f32 v1, v1, v72, v73
	v_mul_f32_e32 v4, 0x3fb8aa3b, v4
	v_max3_f32 v1, v1, v74, v75
	v_exp_f32_e32 v149, v4
	v_sub_f32_e32 v4, v14, v152
	v_max3_f32 v1, v1, v76, v77
	v_add_f32_e32 v2, v140, v141
	v_mul_f32_e32 v4, 0x3fb8aa3b, v4
	v_max3_f32 v1, v1, v78, v79
	v_exp_f32_e32 v150, v4
	v_sub_f32_e32 v4, v15, v152
	v_add_f32_e32 v0, v2, v0
	ds_bpermute_b32 v2, v137, v1
	v_add_f32_e32 v3, v142, v143
	v_mul_f32_e32 v4, 0x3fb8aa3b, v4
	v_exp_f32_e32 v151, v4
	v_add_f32_e32 v4, v144, v145
	v_add_f32_e32 v0, v3, v0
	v_add_f32_e32 v5, v146, v147
	v_add_f32_e32 v0, v4, v0
	v_add_f32_e32 v6, v148, v149
	v_add_f32_e32 v0, v5, v0
	v_add_f32_e32 v5, v6, v0
	s_waitcnt lgkmcnt(0)
; __device__ __forceinline__ unsigned cvt_pk_bf16(float lo, float hi) { f32x2 v = {lo, hi}; bf16x2_t b = __builtin_convertvector(v, bf16x2_t); return __builtin_bit_cast(unsigned, b); }
; __device__ void attn_item(const bf16_t* __restrict__ QX, const bf16_t* __restrict__ KV, bf16_t* __restrict__ O, int tt, int head, LAS unsigned char* lds) {
;     ...
;     mx = fmaxf(mx, __shfl_xor(mx, 32));
;     if (hf == 1) { const float f = __builtin_amdgcn_exp2f((mxp - mx) * 1.4426950408889634f); sum *= f;
; #pragma unroll
;       for (int mt = 0; mt < 4; ++mt) { pf[mt][0] = scale_frag(pf[mt][0], f); pf[mt][1] = scale_frag(pf[mt][1], f); } }
; #pragma unroll
;     for (int mt = 0; mt < 4; ++mt) {
;       u32x4 p0, p1;
; #pragma unroll
;       for (int r = 0; r < 16; r += 2) {
;         const float e0 = __builtin_amdgcn_exp2f((sc[mt][r] - mx) * 1.4426950408889634f), e1 = __builtin_amdgcn_exp2f((sc[mt][r + 1] - mx) * 1.4426950408889634f);
;         sum += e0 + e1; const unsigned pk = cvt_pk_bf16(e0, e1);
;         if (r < 8) p0[r >> 1] = pk; else p1[(r - 8) >> 1] = pk;
	v_max_f32_e32 v0, v2, v2
	v_max_f32_e32 v182, v1, v0
	v_sub_f32_e32 v1, v112, v182
	v_sub_f32_e32 v2, v113, v182
	v_sub_f32_e32 v0, v152, v182
	v_mul_f32_e32 v1, 0x3fb8aa3b, v1
	v_mul_f32_e32 v2, 0x3fb8aa3b, v2
	v_mul_f32_e32 v0, 0x3fb8aa3b, v0
	v_exp_f32_e32 v1, v1
	v_exp_f32_e32 v2, v2
	v_exp_f32_e32 v0, v0
	v_add_f32_e32 v7, v150, v151
	v_sub_f32_e32 v3, v114, v182
	v_sub_f32_e32 v4, v115, v182
	v_add_f32_e32 v5, v7, v5
	v_add_f32_e32 v9, v1, v2
	v_mul_f32_e32 v3, 0x3fb8aa3b, v3
	v_mul_f32_e32 v4, 0x3fb8aa3b, v4
	v_fmac_f32_e32 v9, v5, v0
	v_sub_f32_e32 v5, v116, v182
	v_sub_f32_e32 v6, v117, v182
	v_exp_f32_e32 v3, v3
	v_exp_f32_e32 v4, v4
	v_mul_f32_e32 v5, 0x3fb8aa3b, v5
	v_mul_f32_e32 v6, 0x3fb8aa3b, v6
	v_exp_f32_e32 v5, v5
	v_exp_f32_e32 v6, v6
	v_add_f32_e32 v10, v3, v4
	v_sub_f32_e32 v7, v118, v182
	v_sub_f32_e32 v8, v119, v182
	v_add_f32_e32 v9, v10, v9
	v_add_f32_e32 v10, v5, v6
	v_mul_f32_e32 v7, 0x3fb8aa3b, v7
	v_mul_f32_e32 v8, 0x3fb8aa3b, v8
	v_add_f32_e32 v13, v10, v9
	v_sub_f32_e32 v9, v120, v182
	v_sub_f32_e32 v10, v121, v182
	v_exp_f32_e32 v7, v7
	v_exp_f32_e32 v8, v8
	v_mul_f32_e32 v9, 0x3fb8aa3b, v9
	v_mul_f32_e32 v10, 0x3fb8aa3b, v10
	v_exp_f32_e32 v9, v9
	v_exp_f32_e32 v10, v10
	v_add_f32_e32 v14, v7, v8
	v_sub_f32_e32 v11, v122, v182
	v_sub_f32_e32 v12, v123, v182
	v_add_f32_e32 v13, v14, v13
	v_add_f32_e32 v14, v9, v10
	v_mul_f32_e32 v11, 0x3fb8aa3b, v11
	v_mul_f32_e32 v12, 0x3fb8aa3b, v12
	v_add_f32_e32 v113, v14, v13
	v_sub_f32_e32 v13, v124, v182
	v_sub_f32_e32 v14, v125, v182
	v_exp_f32_e32 v11, v11
	v_exp_f32_e32 v12, v12
	v_mul_f32_e32 v13, 0x3fb8aa3b, v13
	v_mul_f32_e32 v14, 0x3fb8aa3b, v14
	v_exp_f32_e32 v13, v13
	v_exp_f32_e32 v14, v14
	v_add_f32_e32 v114, v11, v12
	v_sub_f32_e32 v96, v96, v182
	v_sub_f32_e32 v15, v126, v182
	v_sub_f32_e32 v112, v127, v182
	v_add_f32_e32 v113, v114, v113
	v_add_f32_e32 v114, v13, v14
	v_mul_f32_e32 v96, 0x3fb8aa3b, v96
	v_mul_f32_e32 v15, 0x3fb8aa3b, v15
	v_mul_f32_e32 v112, 0x3fb8aa3b, v112
	v_add_f32_e32 v117, v114, v113
	v_exp_f32_e32 v113, v96
	v_sub_f32_e32 v96, v97, v182
	v_exp_f32_e32 v15, v15
	v_exp_f32_e32 v112, v112
	v_mul_f32_e32 v96, 0x3fb8aa3b, v96
	v_exp_f32_e32 v114, v96
	v_sub_f32_e32 v96, v98, v182
	v_mul_f32_e32 v96, 0x3fb8aa3b, v96
	v_exp_f32_e32 v115, v96
	v_sub_f32_e32 v96, v99, v182
	v_sub_f32_e32 v98, v100, v182
	v_add_f32_e32 v118, v15, v112
	v_mul_f32_e32 v96, 0x3fb8aa3b, v96
	v_mul_f32_e32 v98, 0x3fb8aa3b, v98
	v_exp_f32_e32 v116, v96
	v_add_f32_e32 v96, v118, v117
	v_exp_f32_e32 v117, v98
	v_sub_f32_e32 v98, v101, v182
	v_mul_f32_e32 v98, 0x3fb8aa3b, v98
	v_exp_f32_e32 v118, v98
	v_sub_f32_e32 v98, v102, v182
	v_sub_f32_e32 v80, v80, v182
	v_mul_f32_e32 v98, 0x3fb8aa3b, v98
	v_mul_f32_e32 v80, 0x3fb8aa3b, v80
	v_exp_f32_e32 v119, v98
	v_sub_f32_e32 v98, v103, v182
	v_exp_f32_e32 v152, v80
	v_sub_f32_e32 v80, v81, v182
	v_mul_f32_e32 v98, 0x3fb8aa3b, v98
	v_mul_f32_e32 v80, 0x3fb8aa3b, v80
	v_exp_f32_e32 v120, v98
	v_sub_f32_e32 v98, v104, v182
	v_exp_f32_e32 v153, v80
	v_sub_f32_e32 v80, v82, v182
	v_sub_f32_e32 v82, v84, v182
	v_mul_f32_e32 v98, 0x3fb8aa3b, v98
	v_mul_f32_e32 v82, 0x3fb8aa3b, v82
	v_exp_f32_e32 v121, v98
	v_sub_f32_e32 v98, v105, v182
	v_exp_f32_e32 v156, v82
	v_sub_f32_e32 v82, v85, v182
	v_mul_f32_e32 v98, 0x3fb8aa3b, v98
	v_mul_f32_e32 v82, 0x3fb8aa3b, v82
	v_exp_f32_e32 v122, v98
	v_sub_f32_e32 v98, v106, v182
	v_exp_f32_e32 v157, v82
	v_sub_f32_e32 v82, v86, v182
	v_sub_f32_e32 v64, v64, v182
	v_mul_f32_e32 v98, 0x3fb8aa3b, v98
	v_mul_f32_e32 v82, 0x3fb8aa3b, v82
	v_mul_f32_e32 v64, 0x3fb8aa3b, v64
	v_exp_f32_e32 v123, v98
	v_sub_f32_e32 v98, v107, v182
	v_exp_f32_e32 v158, v82
	v_sub_f32_e32 v82, v87, v182
	v_exp_f32_e32 v183, v64
	v_sub_f32_e32 v64, v65, v182
	v_mul_f32_e32 v98, 0x3fb8aa3b, v98
	v_mul_f32_e32 v82, 0x3fb8aa3b, v82
	v_mul_f32_e32 v64, 0x3fb8aa3b, v64
	v_exp_f32_e32 v124, v98
	v_sub_f32_e32 v98, v108, v182
	v_exp_f32_e32 v159, v82
	v_sub_f32_e32 v82, v88, v182
	v_exp_f32_e32 v184, v64
	v_sub_f32_e32 v64, v66, v182
	v_sub_f32_e32 v66, v68, v182
	v_mul_f32_e32 v98, 0x3fb8aa3b, v98
	v_mul_f32_e32 v82, 0x3fb8aa3b, v82
	v_mul_f32_e32 v66, 0x3fb8aa3b, v66
	v_exp_f32_e32 v125, v98
	v_sub_f32_e32 v98, v109, v182
	v_exp_f32_e32 v174, v82
	v_sub_f32_e32 v82, v89, v182
	v_exp_f32_e32 v187, v66
	v_sub_f32_e32 v66, v69, v182
	v_mul_f32_e32 v98, 0x3fb8aa3b, v98
	v_mul_f32_e32 v82, 0x3fb8aa3b, v82
	v_mul_f32_e32 v66, 0x3fb8aa3b, v66
	v_exp_f32_e32 v126, v98
	v_sub_f32_e32 v98, v110, v182
	v_exp_f32_e32 v175, v82
	v_sub_f32_e32 v82, v90, v182
	v_exp_f32_e32 v188, v66
	v_sub_f32_e32 v66, v70, v182
	v_add_f32_e32 v97, v113, v114
	v_mul_f32_e32 v98, 0x3fb8aa3b, v98
	v_mul_f32_e32 v82, 0x3fb8aa3b, v82
	v_mul_f32_e32 v66, 0x3fb8aa3b, v66
	v_add_f32_e32 v96, v97, v96
	v_add_f32_e32 v97, v115, v116
	v_exp_f32_e32 v127, v98
	v_sub_f32_e32 v98, v111, v182
	v_exp_f32_e32 v176, v82
	v_sub_f32_e32 v82, v91, v182
	v_exp_f32_e32 v189, v66
	v_sub_f32_e32 v66, v71, v182
	v_add_f32_e32 v96, v97, v96
	v_add_f32_e32 v97, v117, v118
	v_mul_f32_e32 v98, 0x3fb8aa3b, v98
	v_mul_f32_e32 v80, 0x3fb8aa3b, v80
	v_mul_f32_e32 v82, 0x3fb8aa3b, v82
	v_mul_f32_e32 v66, 0x3fb8aa3b, v66
	v_add_f32_e32 v96, v97, v96
	v_add_f32_e32 v97, v119, v120
	v_exp_f32_e32 v111, v98
	v_exp_f32_e32 v154, v80
	v_sub_f32_e32 v80, v83, v182
	v_exp_f32_e32 v177, v82
	v_sub_f32_e32 v82, v92, v182
	v_exp_f32_e32 v190, v66
	v_sub_f32_e32 v66, v72, v182
	v_add_f32_e32 v96, v97, v96
	v_add_f32_e32 v97, v121, v122
	v_mul_f32_e32 v80, 0x3fb8aa3b, v80
	v_mul_f32_e32 v82, 0x3fb8aa3b, v82
	v_mul_f32_e32 v66, 0x3fb8aa3b, v66
	v_add_f32_e32 v96, v97, v96
	v_add_f32_e32 v97, v123, v124
; #define LAS __attribute__((address_space(3)))
; __device__ __forceinline__ unsigned cvt_pk_bf16(float lo, float hi) { f32x2 v = {lo, hi}; bf16x2_t b = __builtin_convertvector(v, bf16x2_t); return __builtin_bit_cast(unsigned, b); }
; __device__ void attn_item(const bf16_t* __restrict__ QX, const bf16_t* __restrict__ KV, bf16_t* __restrict__ O, int tt, int head, LAS unsigned char* lds) {
;     ...
;         const float e0 = __builtin_amdgcn_exp2f((sc[mt][r] - mx) * 1.4426950408889634f), e1 = __builtin_amdgcn_exp2f((sc[mt][r + 1] - mx) * 1.4426950408889634f);
;         sum += e0 + e1; const unsigned pk = cvt_pk_bf16(e0, e1);
;         if (r < 8) p0[r >> 1] = pk; else p1[(r - 8) >> 1] = pk;
;       }
;       pf[hf * 4 + mt][0] = (bf16x8)p0; pf[hf * 4 + mt][1] = (bf16x8)p1;
;     }
;     mxp = mx;
;   }
;   sum += __shfl_xor(sum, 32);
;   const float inv = __builtin_amdgcn_rcpf(sum);
;   __builtin_amdgcn_sched_barrier(0);
;   __syncthreads();
;   __builtin_amdgcn_sched_barrier(0);
; #pragma unroll 4
;   for (int it = 0; it < 16; ++it) { const int q = tid + it * 512, m = q >> 5, c = q & 31;
;     *(LAS u32x4*)(lds + m * VS + c * 16) = *(const u32x4*)(KV + (size_t)(mrow0 + m) * 2048 + 1024 + head * 256 + c * 8); }
	v_exp_f32_e32 v155, v80
	v_exp_f32_e32 v178, v82
	v_sub_f32_e32 v82, v93, v182
	v_exp_f32_e32 v191, v66
	v_sub_f32_e32 v66, v73, v182
	v_add_f32_e32 v96, v97, v96
	v_add_f32_e32 v97, v125, v126
	v_mul_f32_e32 v82, 0x3fb8aa3b, v82
	v_mul_f32_e32 v66, 0x3fb8aa3b, v66
	v_add_f32_e32 v96, v97, v96
	v_add_f32_e32 v97, v127, v111
	v_exp_f32_e32 v179, v82
	v_sub_f32_e32 v82, v94, v182
	v_exp_f32_e32 v192, v66
	v_sub_f32_e32 v66, v74, v182
	v_add_f32_e32 v80, v97, v96
	v_add_f32_e32 v81, v152, v153
	v_mul_f32_e32 v82, 0x3fb8aa3b, v82
	v_mul_f32_e32 v66, 0x3fb8aa3b, v66
	v_add_f32_e32 v80, v81, v80
	v_add_f32_e32 v81, v154, v155
	v_exp_f32_e32 v180, v82
	v_sub_f32_e32 v82, v95, v182
	v_exp_f32_e32 v193, v66
	v_sub_f32_e32 v66, v75, v182
	v_add_f32_e32 v80, v81, v80
	v_add_f32_e32 v81, v156, v157
	v_mul_f32_e32 v82, 0x3fb8aa3b, v82
	v_mul_f32_e32 v64, 0x3fb8aa3b, v64
	v_mul_f32_e32 v66, 0x3fb8aa3b, v66
	v_add_f32_e32 v80, v81, v80
	v_add_f32_e32 v81, v158, v159
	v_exp_f32_e32 v181, v82
	v_exp_f32_e32 v185, v64
	v_sub_f32_e32 v64, v67, v182
	v_exp_f32_e32 v194, v66
	v_sub_f32_e32 v66, v76, v182
	v_add_f32_e32 v80, v81, v80
	v_add_f32_e32 v81, v174, v175
	v_mul_f32_e32 v64, 0x3fb8aa3b, v64
	v_mul_f32_e32 v66, 0x3fb8aa3b, v66
	v_add_f32_e32 v80, v81, v80
	v_add_f32_e32 v81, v176, v177
	v_exp_f32_e32 v186, v64
	v_exp_f32_e32 v195, v66
	v_sub_f32_e32 v66, v77, v182
	v_add_f32_e32 v80, v81, v80
	v_add_f32_e32 v81, v178, v179
	v_mul_f32_e32 v66, 0x3fb8aa3b, v66
	v_add_f32_e32 v80, v81, v80
	v_add_f32_e32 v81, v180, v181
	v_exp_f32_e32 v196, v66
	v_sub_f32_e32 v66, v78, v182
	v_add_f32_e32 v64, v81, v80
	v_add_f32_e32 v65, v183, v184
	v_mul_f32_e32 v66, 0x3fb8aa3b, v66
	v_add_f32_e32 v64, v65, v64
	v_add_f32_e32 v65, v185, v186
	v_exp_f32_e32 v197, v66
	v_sub_f32_e32 v66, v79, v182
	v_add_f32_e32 v64, v65, v64
	v_add_f32_e32 v65, v187, v188
	v_mul_f32_e32 v66, 0x3fb8aa3b, v66
	v_add_f32_e32 v64, v65, v64
	v_add_f32_e32 v65, v189, v190
	v_exp_f32_e32 v198, v66
	v_add_f32_e32 v64, v65, v64
	v_add_f32_e32 v65, v191, v192
	v_add_f32_e32 v64, v65, v64
	v_add_f32_e32 v65, v193, v194
	v_add_f32_e32 v64, v65, v64
	v_add_f32_e32 v65, v195, v196
	v_add_f32_e32 v64, v65, v64
	v_add_f32_e32 v65, v197, v198
	v_add_f32_e32 v182, v65, v64
	ds_bpermute_b32 v137, v137, v182
	s_waitcnt lgkmcnt(0)
	s_barrier
	v_lshrrev_b32_e32 v108, 5, v133
	v_add_u32_e32 v68, s7, v108
	v_ashrrev_i32_e32 v69, 31, v68
	v_lshlrev_b64 v[68:69], 12, v[68:69]
	v_lshl_add_u64 v[68:69], v[128:129], 0, v[68:69]
	v_mad_u32_u24 v70, v108, s54, v132
	s_mov_b64 s[34:35], 0x10000
	v_add_u32_e32 v71, 0x12000, v70
	global_load_dwordx4 v[64:67], v[68:69], off offset:2048
	v_lshl_add_u64 v[68:69], v[68:69], 0, s[34:35]
	global_load_dwordx4 v[72:75], v[68:69], off offset:2048
	v_lshl_add_u64 v[68:69], v[68:69], 0, s[34:35]
	global_load_dwordx4 v[76:79], v[68:69], off offset:2048
	v_lshl_add_u64 v[68:69], v[68:69], 0, s[34:35]
	global_load_dwordx4 v[80:83], v[68:69], off offset:2048
	v_lshl_add_u64 v[68:69], v[68:69], 0, s[34:35]
	global_load_dwordx4 v[84:87], v[68:69], off offset:2048
	v_lshl_add_u64 v[68:69], v[68:69], 0, s[34:35]
	global_load_dwordx4 v[88:91], v[68:69], off offset:2048
	v_lshl_add_u64 v[68:69], v[68:69], 0, s[34:35]
	global_load_dwordx4 v[92:95], v[68:69], off offset:2048
	v_lshl_add_u64 v[68:69], v[68:69], 0, s[34:35]
	global_load_dwordx4 v[96:99], v[68:69], off offset:2048
	v_lshl_add_u64 v[68:69], v[68:69], 0, s[34:35]
	global_load_dwordx4 v[100:103], v[68:69], off offset:2048
	v_lshl_add_u64 v[68:69], v[68:69], 0, s[34:35]
	global_load_dwordx4 v[104:107], v[68:69], off offset:2048
	v_lshl_add_u64 v[68:69], v[68:69], 0, s[34:35]
	global_load_dwordx4 v[200:203], v[68:69], off offset:2048
	v_lshl_add_u64 v[68:69], v[68:69], 0, s[34:35]
	global_load_dwordx4 v[204:207], v[68:69], off offset:2048
	v_lshl_add_u64 v[68:69], v[68:69], 0, s[34:35]
	global_load_dwordx4 v[208:211], v[68:69], off offset:2048
	v_lshl_add_u64 v[68:69], v[68:69], 0, s[34:35]
	global_load_dwordx4 v[232:235], v[68:69], off offset:2048
	v_lshl_add_u64 v[68:69], v[68:69], 0, s[34:35]
	global_load_dwordx4 v[236:239], v[68:69], off offset:2048
	v_lshl_add_u64 v[68:69], v[68:69], 0, s[34:35]
	global_load_dwordx4 v[240:243], v[68:69], off offset:2048
	s_waitcnt vmcnt(15)
	ds_write_b128 v70, v[64:67]
	s_waitcnt vmcnt(14)
	ds_write_b128 v70, v[72:75] offset:9216
	s_waitcnt vmcnt(13)
	ds_write_b128 v70, v[76:79] offset:18432
	s_waitcnt vmcnt(12)
	ds_write_b128 v70, v[80:83] offset:27648
	s_waitcnt vmcnt(11)
	ds_write_b128 v70, v[84:87] offset:36864
	s_waitcnt vmcnt(10)
	ds_write_b128 v70, v[88:91] offset:46080
	s_waitcnt vmcnt(9)
	ds_write_b128 v70, v[92:95] offset:55296
	s_waitcnt vmcnt(8)
	ds_write_b128 v70, v[96:99] offset:64512
	s_waitcnt vmcnt(7)
	ds_write_b128 v71, v[100:103]
	s_waitcnt vmcnt(6)
	ds_write_b128 v71, v[104:107] offset:9216
	s_waitcnt vmcnt(5)
	ds_write_b128 v71, v[200:203] offset:18432
	s_waitcnt vmcnt(4)
	ds_write_b128 v71, v[204:207] offset:27648
	s_waitcnt vmcnt(3)
	ds_write_b128 v71, v[208:211] offset:36864
	s_waitcnt vmcnt(2)
	ds_write_b128 v71, v[232:235] offset:46080
	s_waitcnt vmcnt(1)
	ds_write_b128 v71, v[236:239] offset:55296
	s_waitcnt vmcnt(0)
; __device__ __forceinline__ unsigned cvt_pk_bf16(float lo, float hi) { f32x2 v = {lo, hi}; bf16x2_t b = __builtin_convertvector(v, bf16x2_t); return __builtin_bit_cast(unsigned, b); }
; __device__ void attn_item(const bf16_t* __restrict__ QX, const bf16_t* __restrict__ KV, bf16_t* __restrict__ O, int tt, int head, LAS unsigned char* lds) {
;     ...
;     if (hf == 1) { const float f = __builtin_amdgcn_exp2f((mxp - mx) * 1.4426950408889634f); sum *= f;
; #pragma unroll
;       for (int mt = 0; mt < 4; ++mt) { pf[mt][0] = scale_frag(pf[mt][0], f); pf[mt][1] = scale_frag(pf[mt][1], f); } }
; #pragma unroll
;     for (int mt = 0; mt < 4; ++mt) {
;       u32x4 p0, p1;
; #pragma unroll
;       for (int r = 0; r < 16; r += 2) {
;         const float e0 = __builtin_amdgcn_exp2f((sc[mt][r] - mx) * 1.4426950408889634f), e1 = __builtin_amdgcn_exp2f((sc[mt][r + 1] - mx) * 1.4426950408889634f);
;         sum += e0 + e1; const unsigned pk = cvt_pk_bf16(e0, e1);
;         if (r < 8) p0[r >> 1] = pk; else p1[(r - 8) >> 1] = pk;
;       }
;       pf[hf * 4 + mt][0] = (bf16x8)p0; pf[hf * 4 + mt][1] = (bf16x8)p1;
	ds_write_b128 v71, v[240:243] offset:64512
	s_movk_i32 s12, 0x2000
	v_cvt_pk_bf16_f32 v48, v48, v49
	v_cvt_pk_bf16_f32 v32, v32, v33
	v_cvt_pk_bf16_f32 v33, v34, v35
	v_cvt_pk_bf16_f32 v34, v36, v37
	v_cvt_pk_bf16_f32 v36, v40, v41
	v_cvt_pk_bf16_f32 v40, v16, v17
	v_lshlrev_b32_e32 v16, 16, v48
	v_and_b32_e32 v17, 0xffff0000, v48
	v_cvt_pk_bf16_f32 v49, v50, v51
	v_pk_mul_f32 v[16:17], v[0:1], v[16:17] op_sel_hi:[0,1]
	v_cvt_pk_bf16_f32 v64, v16, v17
	v_lshlrev_b32_e32 v16, 16, v49
	v_and_b32_e32 v17, 0xffff0000, v49
	v_cvt_pk_bf16_f32 v50, v52, v53
	v_pk_mul_f32 v[16:17], v[0:1], v[16:17] op_sel_hi:[0,1]
	v_cvt_pk_bf16_f32 v65, v16, v17
	v_lshlrev_b32_e32 v16, 16, v50
	v_and_b32_e32 v17, 0xffff0000, v50
	v_cvt_pk_bf16_f32 v51, v54, v55
	v_pk_mul_f32 v[16:17], v[0:1], v[16:17] op_sel_hi:[0,1]
	v_cvt_pk_bf16_f32 v66, v16, v17
	v_lshlrev_b32_e32 v16, 16, v51
	v_and_b32_e32 v17, 0xffff0000, v51
	v_cvt_pk_bf16_f32 v52, v56, v57
	v_pk_mul_f32 v[16:17], v[0:1], v[16:17] op_sel_hi:[0,1]
	v_cvt_pk_bf16_f32 v67, v16, v17
	v_lshlrev_b32_e32 v16, 16, v52
	v_and_b32_e32 v17, 0xffff0000, v52
	v_cvt_pk_bf16_f32 v53, v58, v59
	v_pk_mul_f32 v[16:17], v[0:1], v[16:17] op_sel_hi:[0,1]
	v_cvt_pk_bf16_f32 v68, v16, v17
	v_lshlrev_b32_e32 v16, 16, v53
	v_and_b32_e32 v17, 0xffff0000, v53
	v_cvt_pk_bf16_f32 v54, v60, v61
	v_pk_mul_f32 v[16:17], v[0:1], v[16:17] op_sel_hi:[0,1]
	v_cvt_pk_bf16_f32 v69, v16, v17
	v_lshlrev_b32_e32 v16, 16, v54
	v_and_b32_e32 v17, 0xffff0000, v54
	v_cvt_pk_bf16_f32 v55, v62, v63
	v_pk_mul_f32 v[16:17], v[0:1], v[16:17] op_sel_hi:[0,1]
	v_cvt_pk_bf16_f32 v70, v16, v17
	v_lshlrev_b32_e32 v16, 16, v55
	v_and_b32_e32 v17, 0xffff0000, v55
	v_pk_mul_f32 v[16:17], v[0:1], v[16:17] op_sel_hi:[0,1]
	v_cvt_pk_bf16_f32 v71, v16, v17
	v_lshlrev_b32_e32 v16, 16, v32
	v_and_b32_e32 v17, 0xffff0000, v32
	v_pk_mul_f32 v[16:17], v[0:1], v[16:17] op_sel_hi:[0,1]
	v_cvt_pk_bf16_f32 v72, v16, v17
	v_lshlrev_b32_e32 v16, 16, v33
	v_and_b32_e32 v17, 0xffff0000, v33
	v_pk_mul_f32 v[16:17], v[0:1], v[16:17] op_sel_hi:[0,1]
	v_cvt_pk_bf16_f32 v73, v16, v17
	v_lshlrev_b32_e32 v16, 16, v34
	v_and_b32_e32 v17, 0xffff0000, v34
	v_cvt_pk_bf16_f32 v35, v38, v39
	v_pk_mul_f32 v[16:17], v[0:1], v[16:17] op_sel_hi:[0,1]
	v_cvt_pk_bf16_f32 v74, v16, v17
	v_lshlrev_b32_e32 v16, 16, v35
	v_and_b32_e32 v17, 0xffff0000, v35
	v_pk_mul_f32 v[16:17], v[0:1], v[16:17] op_sel_hi:[0,1]
	v_cvt_pk_bf16_f32 v75, v16, v17
	v_lshlrev_b32_e32 v16, 16, v36
	v_and_b32_e32 v17, 0xffff0000, v36
	v_cvt_pk_bf16_f32 v37, v42, v43
	v_pk_mul_f32 v[16:17], v[0:1], v[16:17] op_sel_hi:[0,1]
	v_cvt_pk_bf16_f32 v76, v16, v17
	v_lshlrev_b32_e32 v16, 16, v37
	v_and_b32_e32 v17, 0xffff0000, v37
	v_cvt_pk_bf16_f32 v38, v44, v45
	v_pk_mul_f32 v[16:17], v[0:1], v[16:17] op_sel_hi:[0,1]
	v_cvt_pk_bf16_f32 v77, v16, v17
	v_lshlrev_b32_e32 v16, 16, v38
	v_and_b32_e32 v17, 0xffff0000, v38
	v_cvt_pk_bf16_f32 v39, v46, v47
	v_pk_mul_f32 v[16:17], v[0:1], v[16:17] op_sel_hi:[0,1]
	v_cvt_pk_bf16_f32 v78, v16, v17
	v_lshlrev_b32_e32 v16, 16, v39
	v_and_b32_e32 v17, 0xffff0000, v39
	v_pk_mul_f32 v[16:17], v[0:1], v[16:17] op_sel_hi:[0,1]
	v_cvt_pk_bf16_f32 v79, v16, v17
	v_lshlrev_b32_e32 v16, 16, v40
	v_and_b32_e32 v17, 0xffff0000, v40
	v_cvt_pk_bf16_f32 v18, v18, v19
	v_pk_mul_f32 v[16:17], v[0:1], v[16:17] op_sel_hi:[0,1]
	v_cvt_pk_bf16_f32 v80, v16, v17
	v_lshlrev_b32_e32 v16, 16, v18
	v_and_b32_e32 v17, 0xffff0000, v18
	v_cvt_pk_bf16_f32 v19, v20, v21
	v_pk_mul_f32 v[16:17], v[0:1], v[16:17] op_sel_hi:[0,1]
	v_cvt_pk_bf16_f32 v81, v16, v17
	v_lshlrev_b32_e32 v16, 16, v19
	v_and_b32_e32 v17, 0xffff0000, v19
	v_cvt_pk_bf16_f32 v20, v22, v23
	v_pk_mul_f32 v[16:17], v[0:1], v[16:17] op_sel_hi:[0,1]
	v_cvt_pk_bf16_f32 v82, v16, v17
	v_lshlrev_b32_e32 v16, 16, v20
	v_and_b32_e32 v17, 0xffff0000, v20
	v_cvt_pk_bf16_f32 v21, v24, v25
	v_pk_mul_f32 v[16:17], v[0:1], v[16:17] op_sel_hi:[0,1]
	v_cvt_pk_bf16_f32 v83, v16, v17
	v_lshlrev_b32_e32 v16, 16, v21
	v_and_b32_e32 v17, 0xffff0000, v21
	v_cvt_pk_bf16_f32 v22, v26, v27
	v_pk_mul_f32 v[16:17], v[0:1], v[16:17] op_sel_hi:[0,1]
	v_cvt_pk_bf16_f32 v84, v16, v17
	v_lshlrev_b32_e32 v16, 16, v22
	v_and_b32_e32 v17, 0xffff0000, v22
	v_cvt_pk_bf16_f32 v23, v28, v29
; #define LAS __attribute__((address_space(3)))
; __device__ __forceinline__ unsigned cvt_pk_bf16(float lo, float hi) { f32x2 v = {lo, hi}; bf16x2_t b = __builtin_convertvector(v, bf16x2_t); return __builtin_bit_cast(unsigned, b); }
; __device__ __forceinline__ f32x16 mfma32(bf16x8 a, bf16x8 b, f32x16 c) { return __builtin_amdgcn_mfma_f32_32x32x16_bf16(a, b, c, 0, 0, 0); }
; __device__ void attn_item(const bf16_t* __restrict__ QX, const bf16_t* __restrict__ KV, bf16_t* __restrict__ O, int tt, int head, LAS unsigned char* lds) {
;     ...
;       for (int mt = 0; mt < 4; ++mt) { pf[mt][0] = scale_frag(pf[mt][0], f); pf[mt][1] = scale_frag(pf[mt][1], f); } }
; #pragma unroll
;     for (int mt = 0; mt < 4; ++mt) {
;       u32x4 p0, p1;
; #pragma unroll
;       for (int r = 0; r < 16; r += 2) {
;         const float e0 = __builtin_amdgcn_exp2f((sc[mt][r] - mx) * 1.4426950408889634f), e1 = __builtin_amdgcn_exp2f((sc[mt][r + 1] - mx) * 1.4426950408889634f);
;         sum += e0 + e1; const unsigned pk = cvt_pk_bf16(e0, e1);
;         if (r < 8) p0[r >> 1] = pk; else p1[(r - 8) >> 1] = pk;
;       }
;       pf[hf * 4 + mt][0] = (bf16x8)p0; pf[hf * 4 + mt][1] = (bf16x8)p1;
;     }
;     mxp = mx;
;   }
;   sum += __shfl_xor(sum, 32);
;   const float inv = __builtin_amdgcn_rcpf(sum);
;   __builtin_amdgcn_sched_barrier(0);
;   __syncthreads();
;   __builtin_amdgcn_sched_barrier(0);
; #pragma unroll 4
;   for (int it = 0; it < 16; ++it) { const int q = tid + it * 512, m = q >> 5, c = q & 31;
;     *(LAS u32x4*)(lds + m * VS + c * 16) = *(const u32x4*)(KV + (size_t)(mrow0 + m) * 2048 + 1024 + head * 256 + c * 8); }
;   __syncthreads();
;   __builtin_amdgcn_sched_barrier(0);
; #pragma unroll 1
;   for (int half = 0; half < 2; ++half) {
;     f32x16 acc[4];
; #pragma unroll
;     for (int i = 0; i < 4; ++i) acc[i] = (f32x16){};
;     const unsigned cofs = (unsigned)(half * 128 + 16 * G1 + 4 * p4) * 2u;
; #pragma unroll
;     for (int mt = 0; mt < 8; ++mt)
; #pragma unroll
;       for (int s = 0; s < 2; ++s) {
;         const unsigned r = (unsigned)(mt * 32 + 16 * s + 4 * h + q4);
; #pragma unroll
;         for (int et = 0; et < 4; ++et) acc[et] = mfma32(tr_frag(lds, r * VS + et * 64 + cofs, (r + 8) * VS + et * 64 + cofs), pf[mt][s], acc[et]);
	v_pk_mul_f32 v[16:17], v[0:1], v[16:17] op_sel_hi:[0,1]
	v_cvt_pk_bf16_f32 v85, v16, v17
	v_lshlrev_b32_e32 v16, 16, v23
	v_and_b32_e32 v17, 0xffff0000, v23
	v_cvt_pk_bf16_f32 v24, v30, v31
	v_pk_mul_f32 v[16:17], v[0:1], v[16:17] op_sel_hi:[0,1]
	v_cvt_pk_bf16_f32 v86, v16, v17
	v_lshlrev_b32_e32 v16, 16, v24
	v_and_b32_e32 v17, 0xffff0000, v24
	v_cvt_pk_bf16_f32 v25, v134, v135
	v_pk_mul_f32 v[16:17], v[0:1], v[16:17] op_sel_hi:[0,1]
	v_cvt_pk_bf16_f32 v87, v16, v17
	v_lshlrev_b32_e32 v16, 16, v25
	v_and_b32_e32 v17, 0xffff0000, v25
	v_cvt_pk_bf16_f32 v26, v138, v139
	v_pk_mul_f32 v[16:17], v[0:1], v[16:17] op_sel_hi:[0,1]
	v_cvt_pk_bf16_f32 v88, v16, v17
	v_lshlrev_b32_e32 v16, 16, v26
	v_and_b32_e32 v17, 0xffff0000, v26
	v_cvt_pk_bf16_f32 v27, v140, v141
	v_pk_mul_f32 v[16:17], v[0:1], v[16:17] op_sel_hi:[0,1]
	v_cvt_pk_bf16_f32 v89, v16, v17
	v_lshlrev_b32_e32 v16, 16, v27
	v_and_b32_e32 v17, 0xffff0000, v27
	v_cvt_pk_bf16_f32 v28, v142, v143
	v_pk_mul_f32 v[16:17], v[0:1], v[16:17] op_sel_hi:[0,1]
	v_cvt_pk_bf16_f32 v90, v16, v17
	v_lshlrev_b32_e32 v16, 16, v28
	v_and_b32_e32 v17, 0xffff0000, v28
	v_cvt_pk_bf16_f32 v29, v144, v145
	v_pk_mul_f32 v[16:17], v[0:1], v[16:17] op_sel_hi:[0,1]
	v_cvt_pk_bf16_f32 v91, v16, v17
	v_lshlrev_b32_e32 v16, 16, v29
	v_and_b32_e32 v17, 0xffff0000, v29
	v_cvt_pk_bf16_f32 v30, v146, v147
	v_pk_mul_f32 v[16:17], v[0:1], v[16:17] op_sel_hi:[0,1]
	v_cvt_pk_bf16_f32 v92, v16, v17
	v_lshlrev_b32_e32 v16, 16, v30
	v_and_b32_e32 v17, 0xffff0000, v30
	v_cvt_pk_bf16_f32 v31, v148, v149
	v_pk_mul_f32 v[16:17], v[0:1], v[16:17] op_sel_hi:[0,1]
	v_cvt_pk_bf16_f32 v93, v16, v17
	v_lshlrev_b32_e32 v16, 16, v31
	v_and_b32_e32 v17, 0xffff0000, v31
	v_cvt_pk_bf16_f32 v41, v150, v151
	v_pk_mul_f32 v[16:17], v[0:1], v[16:17] op_sel_hi:[0,1]
	v_cvt_pk_bf16_f32 v94, v16, v17
	v_lshlrev_b32_e32 v16, 16, v41
	v_and_b32_e32 v17, 0xffff0000, v41
	v_pk_mul_f32 v[16:17], v[0:1], v[16:17] op_sel_hi:[0,1]
	v_cvt_pk_bf16_f32 v96, v1, v2
	v_add_f32_e32 v1, v182, v137
	v_rcp_f32_e32 v128, v1
	v_cvt_pk_bf16_f32 v95, v16, v17
	v_cvt_pk_bf16_f32 v97, v3, v4
	v_cvt_pk_bf16_f32 v98, v5, v6
	v_cvt_pk_bf16_f32 v99, v7, v8
	v_cvt_pk_bf16_f32 v100, v9, v10
	v_cvt_pk_bf16_f32 v101, v11, v12
	v_cvt_pk_bf16_f32 v102, v13, v14
	v_cvt_pk_bf16_f32 v103, v15, v112
	v_cvt_pk_bf16_f32 v104, v113, v114
	v_cvt_pk_bf16_f32 v105, v115, v116
	v_cvt_pk_bf16_f32 v106, v117, v118
	v_cvt_pk_bf16_f32 v107, v119, v120
	v_cvt_pk_bf16_f32 v108, v121, v122
	v_cvt_pk_bf16_f32 v109, v123, v124
	v_cvt_pk_bf16_f32 v110, v125, v126
	v_cvt_pk_bf16_f32 v111, v127, v111
	v_cvt_pk_bf16_f32 v112, v152, v153
	v_cvt_pk_bf16_f32 v113, v154, v155
	v_cvt_pk_bf16_f32 v114, v156, v157
	v_cvt_pk_bf16_f32 v115, v158, v159
	v_cvt_pk_bf16_f32 v116, v174, v175
	v_cvt_pk_bf16_f32 v117, v176, v177
	v_cvt_pk_bf16_f32 v118, v178, v179
	v_cvt_pk_bf16_f32 v119, v180, v181
	v_cvt_pk_bf16_f32 v120, v183, v184
	v_cvt_pk_bf16_f32 v121, v185, v186
	v_cvt_pk_bf16_f32 v122, v187, v188
	v_cvt_pk_bf16_f32 v123, v189, v190
	v_cvt_pk_bf16_f32 v124, v191, v192
	v_cvt_pk_bf16_f32 v125, v193, v194
	v_cvt_pk_bf16_f32 v126, v195, v196
	v_cvt_pk_bf16_f32 v127, v197, v198
	v_bfe_u32 v0, v133, 2, 2
	v_and_b32_e32 v2, 16, v133
	s_waitcnt lgkmcnt(0)
	s_barrier
	v_lshlrev_b32_e32 v1, 2, v133
	v_and_or_b32 v132, v1, 12, v2
	v_lshl_or_b32 v2, v136, 2, v0
	v_lshlrev_b64 v[0:1], 11, v[130:131]
	v_lshl_add_u64 v[0:1], s[10:11], 0, v[0:1]
	v_lshl_add_u64 v[0:1], s[22:23], 1, v[0:1]
	v_lshl_add_u64 v[130:131], v[0:1], 0, v[160:161]
	v_mov_b32_e32 v0, 0x14400
	v_mul_u32_u24_e32 v133, 0x240, v2
	v_mad_u32_u24 v138, v2, s54, v0
	v_mov_b32_e32 v0, 0x16800
	v_mad_u32_u24 v134, v2, s54, 0
	v_or_b32_e32 v136, 0x12000, v133
	v_mad_u32_u24 v140, v2, s54, v0
	v_mad_u32_u24 v142, v2, s54, v221
	v_or_b32_e32 v144, 0x1b000, v133
	v_mad_u32_u24 v146, v2, s54, v218
	v_mad_u32_u24 v148, v2, s54, v216
	v_mad_u32_u24 v150, v2, s54, v224
	v_add_u32_e32 v135, 0xfc00, v134
	v_add_u32_e32 v137, 0, v136
	v_add_u32_e32 v139, 0, v138
	v_add_u32_e32 v141, 0, v140
	v_add_u32_e32 v143, 0, v142
	v_add_u32_e32 v145, 0, v144
	v_add_u32_e32 v147, 0, v146
	v_add_u32_e32 v149, 0, v148
	v_add_u32_e32 v151, 0, v150
	v_mov_b32_e32 v129, v128
	s_mov_b32 s20, 0
	s_mov_b64 s[22:23], -1
